# baseline (speedup 1.0000x reference)
.LBB0_220:
	s_add_i32 s12, s11, 0xffff8000
	s_and_b32 s12, s12, 0x8000
	s_lshl_b32 s12, s12, 1
	v_lshl_or_b32 v235, v14, 1, s12
	v_add_u32_e32 v234, v235, v10
	v_add_u32_e32 v235, v235, v8
	ds_read_b128 v[16:19], v234
	ds_read_b128 v[20:23], v235 offset:32768
	ds_read_b128 v[24:27], v235 offset:36864
	ds_read_b128 v[28:31], v235 offset:40960
	ds_read_b128 v[32:35], v235 offset:45056
	ds_read_b128 v[148:151], v234 offset:4096
	s_waitcnt lgkmcnt(4)
	v_mfma_f32_32x32x16_bf16 a[224:239], v[16:19], v[20:23], a[224:239]
	s_waitcnt lgkmcnt(3)
	v_mfma_f32_32x32x16_bf16 a[160:175], v[16:19], v[24:27], a[160:175]
	s_and_b32 s98, s11, 0x8000
	s_lshl_b32 s98, s98, 1
	s_add_i32 s98, s62, s98
	v_lshl_add_u64 v[100:101], v[0:1], 0, s[4:5]
	v_lshl_add_u64 v[104:105], v[100:101], 0, s[16:17]
	s_mov_b32 m0, s98
	s_add_i32 s99, s98, 0x8000
	global_load_lds_dwordx4 v[104:105], off
	s_waitcnt lgkmcnt(2)
	v_mfma_f32_32x32x16_bf16 a[96:111], v[16:19], v[28:31], a[96:111]
	v_lshl_add_u64 v[104:105], v[4:5], 0, s[4:5]
	v_lshl_add_u64 v[114:115], v[104:105], 0, s[38:39]
	s_mov_b32 m0, s99
	s_nop 0
	global_load_lds_dwordx4 v[114:115], off
	s_waitcnt lgkmcnt(1)
	v_mfma_f32_32x32x16_bf16 a[32:47], v[16:19], v[32:35], a[32:47]
	v_lshl_add_u64 v[114:115], v[2:3], 0, s[4:5]
	v_lshl_add_u64 v[118:119], v[114:115], 0, s[30:31]
	s_add_i32 m0, s98, 0x400
	s_nop 0
	global_load_lds_dwordx4 v[118:119], off
	ds_read_b128 v[16:19], v234 offset:16384
	s_waitcnt lgkmcnt(1)
	v_mfma_f32_32x32x16_bf16 a[192:207], v[148:151], v[20:23], a[192:207]
	v_lshl_add_u64 v[118:119], v[6:7], 0, s[4:5]
	v_lshl_add_u64 v[144:145], v[118:119], 0, s[44:45]
	s_add_i32 m0, s98, 0x8400
	s_nop 0
	global_load_lds_dwordx4 v[144:145], off
	v_mfma_f32_32x32x16_bf16 a[128:143], v[148:151], v[24:27], a[128:143]
	v_lshl_add_u64 v[144:145], v[100:101], 0, s[68:69]
	s_add_i32 m0, s98, 0x800
	s_nop 0
	global_load_lds_dwordx4 v[144:145], off
	v_mfma_f32_32x32x16_bf16 a[64:79], v[148:151], v[28:31], a[64:79]
	v_lshl_add_u64 v[144:145], v[104:105], 0, s[2:3]
	s_add_i32 m0, s98, 0x8800
	s_nop 0
	global_load_lds_dwordx4 v[144:145], off
	v_mfma_f32_32x32x16_bf16 a[0:15], v[148:151], v[32:35], a[0:15]
	v_lshl_add_u64 v[144:145], v[114:115], 0, s[70:71]
	s_add_i32 m0, s98, 0xc00
	s_nop 0
	global_load_lds_dwordx4 v[144:145], off
	ds_read_b128 v[148:151], v234 offset:20480
	s_waitcnt lgkmcnt(1)
	v_mfma_f32_32x32x16_bf16 a[240:255], v[16:19], v[20:23], a[240:255]
	v_lshl_add_u64 v[144:145], v[118:119], 0, s[46:47]
	s_add_i32 m0, s98, 0x8c00
	s_nop 0
	global_load_lds_dwordx4 v[144:145], off
	v_mfma_f32_32x32x16_bf16 a[176:191], v[16:19], v[24:27], a[176:191]
	v_lshl_add_u64 v[144:145], v[100:101], 0, s[76:77]
	s_add_i32 m0, s98, 0x1000
	v_lshl_add_u64 v[100:101], v[100:101], 0, s[80:81]
	global_load_lds_dwordx4 v[144:145], off
	v_mfma_f32_32x32x16_bf16 a[112:127], v[16:19], v[28:31], a[112:127]
	v_lshl_add_u64 v[144:145], v[104:105], 0, s[50:51]
	s_add_i32 m0, s98, 0x9000
	s_nop 0
	global_load_lds_dwordx4 v[144:145], off
	v_mfma_f32_32x32x16_bf16 a[48:63], v[16:19], v[32:35], a[48:63]
	v_lshl_add_u64 v[144:145], v[114:115], 0, s[78:79]
	s_add_i32 m0, s98, 0x1400
	s_nop 0
	global_load_lds_dwordx4 v[144:145], off
	v_lshl_or_b32 v235, v13, 1, s12
	v_add_u32_e32 v234, v235, v10
	v_add_u32_e32 v235, v235, v8
	ds_read_b128 v[16:19], v234
	s_waitcnt lgkmcnt(1)
	v_mfma_f32_32x32x16_bf16 a[208:223], v[148:151], v[20:23], a[208:223]
	v_lshl_add_u64 v[144:145], v[118:119], 0, s[52:53]
	s_add_i32 m0, s98, 0x9400
	s_nop 0
	global_load_lds_dwordx4 v[144:145], off
	ds_read_b128 v[20:23], v235 offset:32768
	v_mfma_f32_32x32x16_bf16 a[144:159], v[148:151], v[24:27], a[144:159]
	s_add_i32 m0, s98, 0x1800
	s_nop 0
	global_load_lds_dwordx4 v[100:101], off
	ds_read_b128 v[24:27], v235 offset:36864
	v_mfma_f32_32x32x16_bf16 a[80:95], v[148:151], v[28:31], a[80:95]
	v_lshl_add_u64 v[100:101], v[104:105], 0, s[54:55]
	s_add_i32 m0, s98, 0x9800
	s_nop 0
	global_load_lds_dwordx4 v[100:101], off
	ds_read_b128 v[28:31], v235 offset:40960
	v_mfma_f32_32x32x16_bf16 a[16:31], v[148:151], v[32:35], a[16:31]
	v_lshl_add_u64 v[100:101], v[114:115], 0, s[82:83]
	s_add_i32 m0, s98, 0x1c00
	s_nop 0
	global_load_lds_dwordx4 v[100:101], off
	ds_read_b128 v[32:35], v235 offset:45056
	ds_read_b128 v[148:151], v234 offset:4096
	s_waitcnt lgkmcnt(4)
	v_mfma_f32_32x32x16_bf16 a[224:239], v[16:19], v[20:23], a[224:239]
	v_lshl_add_u64 v[100:101], v[118:119], 0, s[56:57]
	s_add_i32 m0, s98, 0x9c00
	s_nop 0
	global_load_lds_dwordx4 v[100:101], off
	s_waitcnt lgkmcnt(3)
	v_mfma_f32_32x32x16_bf16 a[160:175], v[16:19], v[24:27], a[160:175]
	s_waitcnt lgkmcnt(2)
	v_mfma_f32_32x32x16_bf16 a[96:111], v[16:19], v[28:31], a[96:111]
	s_waitcnt lgkmcnt(1)
	v_mfma_f32_32x32x16_bf16 a[32:47], v[16:19], v[32:35], a[32:47]
	ds_read_b128 v[16:19], v234 offset:16384
	s_waitcnt lgkmcnt(1)
	v_mfma_f32_32x32x16_bf16 a[192:207], v[148:151], v[20:23], a[192:207]
	v_mfma_f32_32x32x16_bf16 a[128:143], v[148:151], v[24:27], a[128:143]
	v_mfma_f32_32x32x16_bf16 a[64:79], v[148:151], v[28:31], a[64:79]
	v_mfma_f32_32x32x16_bf16 a[0:15], v[148:151], v[32:35], a[0:15]
	ds_read_b128 v[148:151], v234 offset:20480
	s_waitcnt lgkmcnt(1)
	v_mfma_f32_32x32x16_bf16 a[240:255], v[16:19], v[20:23], a[240:255]
	v_mfma_f32_32x32x16_bf16 a[176:191], v[16:19], v[24:27], a[176:191]
	v_mfma_f32_32x32x16_bf16 a[112:127], v[16:19], v[28:31], a[112:127]
	v_mfma_f32_32x32x16_bf16 a[48:63], v[16:19], v[32:35], a[48:63]
	v_lshl_or_b32 v235, v12, 1, s12
	v_add_u32_e32 v234, v235, v10
	v_add_u32_e32 v235, v235, v8
	ds_read_b128 v[16:19], v234
	s_waitcnt lgkmcnt(1)
	v_mfma_f32_32x32x16_bf16 a[208:223], v[148:151], v[20:23], a[208:223]
	ds_read_b128 v[20:23], v235 offset:32768
	v_mfma_f32_32x32x16_bf16 a[144:159], v[148:151], v[24:27], a[144:159]
	ds_read_b128 v[24:27], v235 offset:36864
	v_mfma_f32_32x32x16_bf16 a[80:95], v[148:151], v[28:31], a[80:95]
	ds_read_b128 v[28:31], v235 offset:40960
	v_mfma_f32_32x32x16_bf16 a[16:31], v[148:151], v[32:35], a[16:31]
	ds_read_b128 v[32:35], v235 offset:45056
	ds_read_b128 v[148:151], v234 offset:4096
	s_waitcnt lgkmcnt(4)
	v_mfma_f32_32x32x16_bf16 a[224:239], v[16:19], v[20:23], a[224:239]
	s_waitcnt lgkmcnt(3)
	v_mfma_f32_32x32x16_bf16 a[160:175], v[16:19], v[24:27], a[160:175]
	s_waitcnt lgkmcnt(2)
	v_mfma_f32_32x32x16_bf16 a[96:111], v[16:19], v[28:31], a[96:111]
	s_waitcnt lgkmcnt(1)
	v_mfma_f32_32x32x16_bf16 a[32:47], v[16:19], v[32:35], a[32:47]
	ds_read_b128 v[16:19], v234 offset:16384
	s_waitcnt lgkmcnt(1)
	v_mfma_f32_32x32x16_bf16 a[192:207], v[148:151], v[20:23], a[192:207]
	v_mfma_f32_32x32x16_bf16 a[128:143], v[148:151], v[24:27], a[128:143]
	v_mfma_f32_32x32x16_bf16 a[64:79], v[148:151], v[28:31], a[64:79]
	v_mfma_f32_32x32x16_bf16 a[0:15], v[148:151], v[32:35], a[0:15]
	ds_read_b128 v[148:151], v234 offset:20480
	s_waitcnt lgkmcnt(1)
	v_mfma_f32_32x32x16_bf16 a[240:255], v[16:19], v[20:23], a[240:255]
	v_mfma_f32_32x32x16_bf16 a[176:191], v[16:19], v[24:27], a[176:191]
	v_mfma_f32_32x32x16_bf16 a[112:127], v[16:19], v[28:31], a[112:127]
	v_mfma_f32_32x32x16_bf16 a[48:63], v[16:19], v[32:35], a[48:63]
	v_lshl_or_b32 v235, v11, 1, s12
	v_add_u32_e32 v234, v235, v10
	v_add_u32_e32 v235, v235, v8
	ds_read_b128 v[16:19], v234
	s_waitcnt lgkmcnt(1)
	v_mfma_f32_32x32x16_bf16 a[208:223], v[148:151], v[20:23], a[208:223]
	ds_read_b128 v[20:23], v235 offset:32768
	v_mfma_f32_32x32x16_bf16 a[144:159], v[148:151], v[24:27], a[144:159]
	ds_read_b128 v[24:27], v235 offset:36864
	v_mfma_f32_32x32x16_bf16 a[80:95], v[148:151], v[28:31], a[80:95]
	ds_read_b128 v[28:31], v235 offset:40960
	v_mfma_f32_32x32x16_bf16 a[16:31], v[148:151], v[32:35], a[16:31]
	ds_read_b128 v[32:35], v235 offset:45056
	ds_read_b128 v[148:151], v234 offset:4096
	s_waitcnt lgkmcnt(4)
	v_mfma_f32_32x32x16_bf16 a[224:239], v[16:19], v[20:23], a[224:239]
	s_waitcnt lgkmcnt(3)
	v_mfma_f32_32x32x16_bf16 a[160:175], v[16:19], v[24:27], a[160:175]
	s_waitcnt lgkmcnt(2)
	v_mfma_f32_32x32x16_bf16 a[96:111], v[16:19], v[28:31], a[96:111]
	s_waitcnt lgkmcnt(1)
	v_mfma_f32_32x32x16_bf16 a[32:47], v[16:19], v[32:35], a[32:47]
	ds_read_b128 v[16:19], v234 offset:16384
	s_waitcnt lgkmcnt(1)
	v_mfma_f32_32x32x16_bf16 a[192:207], v[148:151], v[20:23], a[192:207]
	v_mfma_f32_32x32x16_bf16 a[128:143], v[148:151], v[24:27], a[128:143]
	v_mfma_f32_32x32x16_bf16 a[64:79], v[148:151], v[28:31], a[64:79]
	v_mfma_f32_32x32x16_bf16 a[0:15], v[148:151], v[32:35], a[0:15]
	ds_read_b128 v[148:151], v234 offset:20480
	s_waitcnt lgkmcnt(1)
	v_mfma_f32_32x32x16_bf16 a[240:255], v[16:19], v[20:23], a[240:255]
	v_mfma_f32_32x32x16_bf16 a[176:191], v[16:19], v[24:27], a[176:191]
	v_mfma_f32_32x32x16_bf16 a[112:127], v[16:19], v[28:31], a[112:127]
	v_mfma_f32_32x32x16_bf16 a[48:63], v[16:19], v[32:35], a[48:63]
	s_waitcnt vmcnt(0)
	s_waitcnt vmcnt(0) lgkmcnt(0)
	s_barrier
	s_add_u32 s4, s4, 0x80
	s_addc_u32 s5, s5, 0
	s_add_i32 s11, s11, 0x8000
	s_cmpk_lg_i32 s4, 0x780
	v_mfma_f32_32x32x16_bf16 a[208:223], v[148:151], v[20:23], a[208:223]
	v_mfma_f32_32x32x16_bf16 a[144:159], v[148:151], v[24:27], a[144:159]
	v_mfma_f32_32x32x16_bf16 a[80:95], v[148:151], v[28:31], a[80:95]
	v_mfma_f32_32x32x16_bf16 a[16:31], v[148:151], v[32:35], a[16:31]
	s_cbranch_scc1 .LBB0_220
	v_lshlrev_b32_e32 v4, 1, v14
	s_mov_b32 s4, 0x10000
	v_add3_u32 v9, v10, v4, s4
	ds_read_b128 v[0:3], v9
	ds_read_b128 v[36:39], v9 offset:20480
	s_mov_b32 s5, 0x18000
	v_add3_u32 v22, v8, v4, s5
	ds_read_b128 v[4:7], v22
	ds_read_b128 v[14:17], v22 offset:4096
	ds_read_b128 v[18:21], v22 offset:8192
	ds_read_b128 v[124:127], v22 offset:12288
	s_waitcnt lgkmcnt(3)
	v_mfma_f32_32x32x16_bf16 a[224:239], v[0:3], v[4:7], a[224:239]
	v_lshlrev_b32_e32 v11, 1, v11
	s_waitcnt lgkmcnt(2)
	v_mfma_f32_32x32x16_bf16 a[160:175], v[0:3], v[14:17], a[160:175]
	s_waitcnt lgkmcnt(1)
	v_mfma_f32_32x32x16_bf16 a[96:111], v[0:3], v[18:21], a[96:111]
	s_waitcnt lgkmcnt(0)
	v_mfma_f32_32x32x16_bf16 a[32:47], v[0:3], v[124:127], a[32:47]
	ds_read_b128 v[0:3], v9 offset:4096
	s_waitcnt lgkmcnt(0)
	v_mfma_f32_32x32x16_bf16 a[192:207], v[0:3], v[4:7], a[192:207]
	v_mfma_f32_32x32x16_bf16 a[128:143], v[0:3], v[14:17], a[128:143]
	v_mfma_f32_32x32x16_bf16 a[64:79], v[0:3], v[18:21], a[64:79]
	v_mfma_f32_32x32x16_bf16 a[0:15], v[0:3], v[124:127], a[0:15]
	ds_read_b128 v[0:3], v9 offset:16384
	s_waitcnt lgkmcnt(0)
	v_mfma_f32_32x32x16_bf16 a[240:255], v[0:3], v[4:7], a[240:255]
	v_mfma_f32_32x32x16_bf16 a[208:223], v[36:39], v[4:7], a[208:223]
	v_lshlrev_b32_e32 v4, 1, v13
	v_add3_u32 v9, v10, v4, s4
	v_add3_u32 v4, v8, v4, s5
	ds_read_b128 v[40:43], v4
	ds_read_b128 v[32:35], v4 offset:4096
	ds_read_b128 v[140:143], v4 offset:8192
	ds_read_b128 v[180:183], v4 offset:12288
	v_mfma_f32_32x32x16_bf16 a[176:191], v[0:3], v[14:17], a[176:191]
	v_lshlrev_b32_e32 v4, 1, v12
	v_mfma_f32_32x32x16_bf16 a[112:127], v[0:3], v[18:21], a[112:127]
	v_mfma_f32_32x32x16_bf16 a[48:63], v[0:3], v[124:127], a[48:63]
	ds_read_b128 v[0:3], v9
	v_mfma_f32_32x32x16_bf16 a[144:159], v[36:39], v[14:17], a[144:159]
	v_add3_u32 v16, v10, v4, s4
	v_add3_u32 v10, v10, v11, s4
	v_add3_u32 v17, v8, v4, s5
	ds_read_b128 v[4:7], v10
	ds_read_b128 v[48:51], v17
	s_mov_b32 s4, 0
	s_waitcnt lgkmcnt(2)
	v_mfma_f32_32x32x16_bf16 a[224:239], v[0:3], v[40:43], a[224:239]
	v_mfma_f32_32x32x16_bf16 a[160:175], v[0:3], v[32:35], a[160:175]
	v_mfma_f32_32x32x16_bf16 a[96:111], v[0:3], v[140:143], a[96:111]
	v_mfma_f32_32x32x16_bf16 a[32:47], v[0:3], v[180:183], a[32:47]
	ds_read_b128 v[0:3], v9 offset:4096
	s_waitcnt lgkmcnt(0)
	v_mfma_f32_32x32x16_bf16 a[192:207], v[0:3], v[40:43], a[192:207]
	v_mfma_f32_32x32x16_bf16 a[128:143], v[0:3], v[32:35], a[128:143]
	v_mfma_f32_32x32x16_bf16 a[64:79], v[0:3], v[140:143], a[64:79]
	v_mfma_f32_32x32x16_bf16 a[0:15], v[0:3], v[180:183], a[0:15]
	ds_read_b128 v[0:3], v9 offset:16384
	s_waitcnt lgkmcnt(0)
	v_mfma_f32_32x32x16_bf16 a[240:255], v[0:3], v[40:43], a[240:255]
	v_mfma_f32_32x32x16_bf16 a[176:191], v[0:3], v[32:35], a[176:191]
	v_mfma_f32_32x32x16_bf16 a[112:127], v[0:3], v[140:143], a[112:127]
	v_mfma_f32_32x32x16_bf16 a[48:63], v[0:3], v[180:183], a[48:63]
	ds_read_b128 v[0:3], v16
	v_mfma_f32_32x32x16_bf16 a[80:95], v[36:39], v[18:21], a[80:95]
	v_add3_u32 v18, v8, v11, s5
	ds_read_b128 v[44:47], v18
	ds_read_b128 v[28:31], v9 offset:20480
	ds_read_b128 v[12:15], v16 offset:4096
	ds_read_b128 v[64:67], v17 offset:4096
	ds_read_b128 v[68:71], v16 offset:16384
	ds_read_b128 v[238:241], v16 offset:20480
	ds_read_b128 v[52:55], v17 offset:8192
	ds_read_b128 v[248:251], v17 offset:12288
	ds_read_b128 v[82:85], v10 offset:4096
	ds_read_b128 v[60:63], v18 offset:4096
	ds_read_b128 v[72:75], v10 offset:16384
	ds_read_b128 v[8:11], v10 offset:20480
	ds_read_b128 v[56:59], v18 offset:8192
	ds_read_b128 v[20:23], v18 offset:12288
	s_waitcnt vmcnt(0)
	s_waitcnt lgkmcnt(0)
	s_barrier
	v_mfma_f32_32x32x16_bf16 a[224:239], v[0:3], v[48:51], a[224:239]
	s_mov_b32 s5, 0
	v_mfma_f32_32x32x16_bf16 a[160:175], v[0:3], v[64:67], a[160:175]
	v_mfma_f32_32x32x16_bf16 a[96:111], v[0:3], v[52:55], a[96:111]
	v_mfma_f32_32x32x16_bf16 a[32:47], v[0:3], v[248:251], a[32:47]
	v_mfma_f32_32x32x16_bf16 a[240:255], v[68:71], v[48:51], a[240:255]
	v_mfma_f32_32x32x16_bf16 a[176:191], v[68:71], v[64:67], a[176:191]
	v_mfma_f32_32x32x16_bf16 a[112:127], v[68:71], v[52:55], a[112:127]
	v_mfma_f32_32x32x16_bf16 a[48:63], v[68:71], v[248:251], a[48:63]
	v_mfma_f32_32x32x16_bf16 a[224:239], v[4:7], v[44:47], a[224:239]
	v_mfma_f32_32x32x16_bf16 a[160:175], v[4:7], v[60:63], a[160:175]
	s_nop 10
	v_accvgpr_read_b32 v117, a227
	v_accvgpr_read_b32 v116, a226
	v_accvgpr_read_b32 v103, a229
	v_mfma_f32_32x32x16_bf16 a[96:111], v[4:7], v[56:59], a[96:111]
	v_accvgpr_read_b32 v102, a228
	v_accvgpr_read_b32 v227, a239
	v_accvgpr_read_b32 v226, a238
	v_accvgpr_read_b32 v229, a237
	v_accvgpr_read_b32 v228, a236
	v_accvgpr_read_b32 v253, a235
	v_accvgpr_read_b32 v252, a234
	v_mfma_f32_32x32x16_bf16 a[32:47], v[4:7], v[20:23], a[32:47]
	v_mbcnt_lo_u32_b32 v4, -1, s4
	v_mbcnt_hi_u32_b32 v16, -1, v4
	v_or_b32_e32 v4, s60, v16
	v_and_b32_e32 v5, 31, v16
	v_lshrrev_b32_e32 v16, 3, v16
	s_and_b32 s4, s10, 3
	s_cmp_gt_i32 s10, 3
	v_mfma_f32_32x32x16_bf16 a[192:207], v[12:15], v[48:51], a[192:207]
	s_cselect_b64 vcc, -1, 0
	v_accvgpr_read_b32 v81, a233
	v_accvgpr_read_b32 v80, a232
	v_accvgpr_read_b32 v79, a231
	v_accvgpr_read_b32 v99, a39
	v_accvgpr_read_b32 v98, a38
	v_accvgpr_read_b32 v129, a35
	v_mfma_f32_32x32x16_bf16 a[128:143], v[12:15], v[64:67], a[128:143]
	v_accvgpr_read_b32 v128, a34
	v_accvgpr_read_b32 v78, a230
	v_accvgpr_read_b32 v131, a175
	v_accvgpr_read_b32 v130, a174
	v_accvgpr_read_b32 v133, a173
	v_accvgpr_read_b32 v132, a172
	v_accvgpr_read_b32 v111, a171
	v_mfma_f32_32x32x16_bf16 a[64:79], v[12:15], v[52:55], a[64:79]
	v_accvgpr_read_b32 v110, a170
	v_accvgpr_read_b32 v113, a169
	v_accvgpr_read_b32 v112, a168
	v_accvgpr_read_b32 v135, a167
	v_accvgpr_read_b32 v134, a166
	v_accvgpr_read_b32 v121, a165
	v_accvgpr_read_b32 v120, a164
	v_mfma_f32_32x32x16_bf16 a[0:15], v[12:15], v[248:251], a[0:15]
	v_lshlrev_b32_e32 v12, 1, v4
	v_ashrrev_i32_e32 v4, 1, v4
	v_and_b32_e32 v24, 0xffffffc0, v4
	v_ashrrev_i32_e32 v25, 31, v24
	v_accvgpr_read_b32 v109, a163
	v_accvgpr_read_b32 v108, a162
	v_accvgpr_read_b32 v209, a111
	v_mfma_f32_32x32x16_bf16 a[240:255], v[72:75], v[44:47], a[240:255]
	v_accvgpr_read_b32 v208, a110
	v_accvgpr_read_b32 v213, a109
	v_accvgpr_read_b32 v212, a108
	v_accvgpr_read_b32 v219, a107
	v_accvgpr_read_b32 v218, a106
	v_accvgpr_read_b32 v221, a105
	v_accvgpr_read_b32 v220, a104
	v_mfma_f32_32x32x16_bf16 a[176:191], v[72:75], v[60:63], a[176:191]
	v_accvgpr_read_b32 v203, a103
	v_accvgpr_read_b32 v202, a102
	v_accvgpr_read_b32 v205, a101
	v_accvgpr_read_b32 v204, a100
	v_accvgpr_read_b32 v139, a243
	v_accvgpr_read_b32 v138, a242
	v_accvgpr_read_b32 v123, a245
	v_mfma_f32_32x32x16_bf16 a[112:127], v[72:75], v[56:59], a[112:127]
	v_accvgpr_read_b32 v122, a244
	v_accvgpr_read_b32 v173, a99
	v_accvgpr_read_b32 v172, a98
	v_accvgpr_read_b32 v89, a47
	v_accvgpr_read_b32 v88, a46
	v_accvgpr_read_b32 v91, a45
	v_accvgpr_read_b32 v90, a44
	v_mfma_f32_32x32x16_bf16 a[48:63], v[72:75], v[20:23], a[48:63]
	v_and_or_b32 v74, v12, s14, v5
	v_lshlrev_b64 v[4:5], 2, v[24:25]
	v_and_b32_e32 v25, 4, v16
	v_lshl_add_u64 v[12:13], s[0:1], 0, v[4:5]
	v_lshlrev_b32_e32 v94, 2, v25
	v_lshl_add_u64 v[4:5], s[6:7], 0, v[4:5]
	v_lshl_add_u64 v[186:187], v[4:5], 0, v[94:95]
	v_or_b32_e32 v4, s66, v74
	v_lshl_add_u64 v[184:185], v[12:13], 0, v[94:95]
	v_lshlrev_b32_e32 v94, 9, v4
	v_mfma_f32_32x32x16_bf16 a[144:159], v[28:31], v[32:35], a[144:159]
	v_lshl_add_u64 v[68:69], v[186:187], 0, v[94:95]
	v_lshl_add_u64 v[72:73], v[184:185], 0, v[94:95]
	global_load_dwordx4 v[32:35], v[68:69], off
	v_or_b32_e32 v24, v24, v25
	v_accvgpr_read_b32 v87, a43
	v_accvgpr_read_b32 v86, a42
	v_accvgpr_read_b32 v97, a41
	v_mfma_f32_32x32x16_bf16 a[208:223], v[28:31], v[40:43], a[208:223]
	global_load_dwordx4 v[40:43], v[72:73], off
	v_accvgpr_read_b32 v96, a40
	v_accvgpr_read_b32 v107, a37
	v_accvgpr_read_b32 v106, a36
	v_accvgpr_read_b32 v3, a253
	v_accvgpr_read_b32 v2, a252
	v_accvgpr_read_b32 v7, a249
	v_mfma_f32_32x32x16_bf16 a[144:159], v[238:241], v[64:67], a[144:159]
	global_load_dwordx4 v[64:67], v[68:69], off offset:32
	global_load_dwordx4 v[16:19], v[72:73], off offset:32
	v_accvgpr_read_b32 v6, a248
	v_accvgpr_read_b32 v15, a247
	v_accvgpr_read_b32 v14, a246
	v_accvgpr_read_b32 v147, a191
	v_accvgpr_read_b32 v146, a190
	v_accvgpr_read_b32 v155, a189
	v_mfma_f32_32x32x16_bf16 a[16:31], v[36:39], v[124:127], a[16:31]
	v_accvgpr_read_b32 v154, a188
	v_accvgpr_read_b32 v153, a187
	v_accvgpr_read_b32 v152, a186
	v_accvgpr_read_b32 v137, a185
	v_accvgpr_read_b32 v136, a184
	v_accvgpr_read_b32 v165, a183
	v_accvgpr_read_b32 v164, a182
	v_mfma_f32_32x32x16_bf16 a[80:95], v[28:31], v[140:143], a[80:95]
	v_accvgpr_read_b32 v207, a181
	v_accvgpr_read_b32 v206, a180
	v_accvgpr_read_b32 v71, a179
	v_accvgpr_read_b32 v70, a178
	v_accvgpr_read_b32 v243, a127
	v_accvgpr_read_b32 v242, a126
	v_accvgpr_read_b32 v245, a125
	v_mfma_f32_32x32x16_bf16 a[16:31], v[28:31], v[180:183], a[16:31]
	v_mov_b32_e32 v30, 0x3d800000
	v_accvgpr_read_b32 v244, a124
	v_accvgpr_read_b32 v247, a123
	v_accvgpr_read_b32 v246, a122
	v_accvgpr_read_b32 v237, a121
	v_accvgpr_read_b32 v236, a120
	v_accvgpr_read_b32 v225, a119
	v_mfma_f32_32x32x16_bf16 a[208:223], v[238:241], v[48:51], a[208:223]
	v_cndmask_b32_e32 v50, 1.0, v30, vcc
	v_accvgpr_read_b32 v224, a118
	v_accvgpr_read_b32 v233, a117
	v_accvgpr_read_b32 v232, a116
	v_accvgpr_read_b32 v217, a115
	v_accvgpr_read_b32 v216, a114
	v_accvgpr_read_b32 v125, a63
	v_mfma_f32_32x32x16_bf16 a[80:95], v[238:241], v[52:55], a[80:95]
	v_accvgpr_read_b32 v124, a62
	v_accvgpr_read_b32 v127, a61
	v_accvgpr_read_b32 v126, a60
	v_accvgpr_read_b32 v141, a59
	v_accvgpr_read_b32 v140, a58
	v_accvgpr_read_b32 v143, a57
	v_accvgpr_read_b32 v142, a56
	v_mfma_f32_32x32x16_bf16 a[16:31], v[238:241], v[248:251], a[16:31]
	v_accvgpr_read_b32 v161, a55
	v_accvgpr_read_b32 v160, a54
	v_accvgpr_read_b32 v167, a53
	v_accvgpr_read_b32 v166, a52
	v_accvgpr_read_b32 v193, a51
	v_accvgpr_read_b32 v192, a50
	v_accvgpr_read_b32 v77, a255
	v_mfma_f32_32x32x16_bf16 a[0:15], v[82:85], v[20:23], a[0:15]
	v_accvgpr_read_b32 v76, a254
	s_waitcnt vmcnt(3)
	v_mul_f32_e64 v26, v116, v34
	v_mul_f32_e64 v27, v117, v35
	v_mfma_f32_32x32x16_bf16 a[208:223], v[8:11], v[44:47], a[208:223]
	s_nop 6
	v_accvgpr_read_b32 v1, a15
	v_accvgpr_read_b32 v0, a14
	v_accvgpr_write_b32 a15, v1
	v_accvgpr_write_b32 a14, v0
	s_waitcnt vmcnt(2)
	v_pk_fma_f32 v[26:27], v[138:139], v[42:43], v[26:27]
	v_accvgpr_read_b32 v1, a13
	v_accvgpr_read_b32 v0, a12
	v_mfma_f32_32x32x16_bf16 a[144:159], v[8:11], v[60:63], a[144:159]
	v_accvgpr_write_b32 a13, v1
	v_accvgpr_write_b32 a12, v0
	v_accvgpr_read_b32 v1, a9
	v_accvgpr_read_b32 v0, a8
	v_accvgpr_write_b32 a39, v1
	v_accvgpr_read_b32 v93, a3
	v_accvgpr_read_b32 v92, a2
	v_mfma_f32_32x32x16_bf16 a[80:95], v[8:11], v[56:59], a[80:95]
	v_accvgpr_write_b32 a38, v0
	v_accvgpr_read_b32 v1, a251
	v_accvgpr_read_b32 v0, a250
	v_accvgpr_read_b32 v49, a219
	v_accvgpr_read_b32 v48, a218
	v_accvgpr_read_b32 v37, a215
	v_accvgpr_read_b32 v36, a214
	v_mfma_f32_32x32x16_bf16 a[16:31], v[8:11], v[20:23], a[16:31]
	v_accvgpr_read_b32 v10, a240
	v_accvgpr_read_b32 v8, a224
	v_accvgpr_read_b32 v11, a241
	v_accvgpr_read_b32 v9, a225
	v_mul_f32_e64 v20, v10, v32
	v_mul_f32_e64 v21, v11, v33
	v_pk_mul_f32 v[22:23], v[138:139], v[34:35]
	v_pk_fma_f32 v[20:21], v[8:9], v[40:41], v[20:21] neg_lo:[0,0,1] neg_hi:[0,0,1]
	v_mfma_f32_32x32x16_bf16 a[192:207], v[82:85], v[44:47], a[192:207]
	v_mul_f32_e64 v8, v8, v32
	v_mul_f32_e64 v9, v9, v33
	v_fma_f32 v22, v116, v42, -v22
	v_fma_f32 v23, v117, v43, -v23
	v_fma_f32 v8, v10, v40, v8
	v_fma_f32 v9, v11, v41, v9
	v_pk_mul_f32 v[32:33], v[50:51], v[20:21] op_sel_hi:[0,1]
	v_pk_mul_f32 v[20:21], v[50:51], v[8:9] op_sel_hi:[0,1]
	v_pk_mul_f32 v[30:31], v[50:51], v[22:23] op_sel_hi:[0,1]
	v_pk_mul_f32 v[22:23], v[50:51], v[26:27] op_sel_hi:[0,1]
	v_mfma_f32_32x32x16_bf16 a[128:143], v[82:85], v[60:63], a[128:143]
	v_lshlrev_b32_e32 v51, 1, v24
	v_cvt_pk_bf16_f32 v8, v32, v33
	v_cvt_pk_bf16_f32 v9, v30, v31
	v_mad_u32_u24 v75, v74, s25, v51
	v_accvgpr_read_b32 v47, a31
	v_accvgpr_read_b32 v46, a30
	v_accvgpr_write_b32 a35, v33
	v_mfma_f32_32x32x16_bf16 a[64:79], v[82:85], v[56:59], a[64:79]
	v_accvgpr_read_b32 v83, a5
	v_accvgpr_read_b32 v82, a4
	v_accvgpr_write_b32 a4, v20
	v_accvgpr_write_b32 a5, v21
	v_cvt_pk_bf16_f32 v20, v20, v21
	v_cvt_pk_bf16_f32 v21, v22, v23
	ds_write2_b64 v75, v[8:9], v[20:21] offset1:32
	s_waitcnt vmcnt(1)
	v_pk_mul_f32 v[8:9], v[122:123], v[64:65]
	v_accvgpr_write_b32 a30, v30
	s_waitcnt vmcnt(0)
	v_pk_fma_f32 v[20:21], v[102:103], v[16:17], v[8:9] neg_lo:[0,0,1] neg_hi:[0,0,1]
	v_pk_mul_f32 v[8:9], v[102:103], v[64:65]
	v_accvgpr_write_b32 a2, v22
	v_pk_fma_f32 v[16:17], v[122:123], v[16:17], v[8:9]
	v_accvgpr_read_b32 v169, a207
	v_accvgpr_read_b32 v168, a206
	v_accvgpr_read_b32 v119, a205
	v_accvgpr_read_b32 v118, a204
	v_accvgpr_read_b32 v115, a203
	v_accvgpr_read_b32 v114, a202
	v_accvgpr_read_b32 v105, a201
	v_accvgpr_read_b32 v104, a200
	v_accvgpr_read_b32 v101, a199
	v_accvgpr_read_b32 v100, a198
	v_accvgpr_read_b32 v211, a197
	v_accvgpr_read_b32 v210, a196
	v_accvgpr_read_b32 v235, a195
	v_accvgpr_read_b32 v234, a194
	v_accvgpr_read_b32 v175, a143
	v_accvgpr_read_b32 v174, a142
	v_accvgpr_read_b32 v195, a141
	v_accvgpr_read_b32 v194, a140
	v_accvgpr_read_b32 v177, a139
	v_accvgpr_read_b32 v176, a138
	v_accvgpr_read_b32 v179, a137
	v_accvgpr_read_b32 v178, a136
	v_accvgpr_read_b32 v157, a135
	v_accvgpr_read_b32 v156, a134
	v_accvgpr_read_b32 v159, a133
	v_accvgpr_read_b32 v158, a132
	v_accvgpr_read_b32 v145, a131
	v_accvgpr_read_b32 v144, a130
	v_accvgpr_read_b32 v149, a79
	v_accvgpr_read_b32 v148, a78
	v_accvgpr_read_b32 v151, a77
	v_accvgpr_read_b32 v150, a76
	v_accvgpr_read_b32 v163, a75
	v_accvgpr_read_b32 v162, a74
	v_accvgpr_read_b32 v171, a73
	v_accvgpr_read_b32 v170, a72
	v_accvgpr_read_b32 v189, a71
	v_accvgpr_read_b32 v188, a70
	v_accvgpr_read_b32 v191, a69
	v_accvgpr_read_b32 v190, a68
	v_accvgpr_read_b32 v215, a67
	v_accvgpr_read_b32 v214, a66
	v_accvgpr_read_b32 v85, a7
	v_accvgpr_read_b32 v84, a6
	v_accvgpr_read_b32 v45, a223
	v_accvgpr_read_b32 v44, a222
	v_accvgpr_read_b32 v63, a217
	v_accvgpr_read_b32 v62, a216
	v_accvgpr_read_b32 v39, a213
	v_accvgpr_read_b32 v38, a212
	v_accvgpr_read_b32 v29, a211
	v_accvgpr_read_b32 v28, a210
	v_accvgpr_read_b32 v197, a157
	v_accvgpr_read_b32 v196, a156
	v_accvgpr_read_b32 v5, a155
	v_accvgpr_read_b32 v4, a154
	v_accvgpr_read_b32 v199, a153
	v_accvgpr_read_b32 v198, a152
	v_accvgpr_read_b32 v201, a151
	v_accvgpr_read_b32 v200, a150
	v_accvgpr_read_b32 v183, a149
	v_accvgpr_read_b32 v182, a148
	v_accvgpr_read_b32 v181, a147
	v_accvgpr_read_b32 v180, a146
	v_accvgpr_read_b32 v223, a95
	v_accvgpr_read_b32 v222, a94
	v_accvgpr_read_b32 v231, a93
	v_accvgpr_read_b32 v230, a92
	v_accvgpr_read_b32 v239, a91
	v_accvgpr_read_b32 v238, a90
	v_accvgpr_read_b32 v241, a89
	v_accvgpr_read_b32 v240, a88
	v_accvgpr_read_b32 v249, a87
	v_accvgpr_read_b32 v248, a86
	v_accvgpr_read_b32 v251, a85
	v_accvgpr_read_b32 v250, a84
	v_accvgpr_write_b32 a34, v32
	v_accvgpr_write_b32 a31, v31
	v_accvgpr_write_b32 a3, v23
	v_accvgpr_read_b32 v57, a29
	v_accvgpr_read_b32 v56, a28
	v_accvgpr_read_b32 v8, a26
	v_accvgpr_read_b32 v103, a25
	v_accvgpr_read_b32 v102, a24
	v_accvgpr_read_b32 v117, a23
	v_accvgpr_read_b32 v116, a22
	v_accvgpr_read_b32 v123, a21
	v_accvgpr_read_b32 v122, a20
	v_accvgpr_read_b32 v139, a19
	v_accvgpr_read_b32 v138, a18
	v_pk_mul_f32 v[24:25], v[50:51], v[20:21] op_sel_hi:[0,1]
	v_pk_mul_f32 v[20:21], v[50:51], v[16:17] op_sel_hi:[0,1]
	v_accvgpr_mov_b32 a37, a11
	v_accvgpr_mov_b32 a36, a10
	v_accvgpr_read_b32 v61, a221
	v_accvgpr_read_b32 v60, a220
	v_accvgpr_read_b32 v13, a159
	v_accvgpr_read_b32 v12, a158
	v_accvgpr_read_b32 v11, a83
	v_accvgpr_read_b32 v10, a82
	v_accvgpr_read_b32 v9, a27
	global_load_dwordx4 a[194:197], v[72:73], off offset:64
	global_load_dwordx4 a[198:201], v[68:69], off offset:64
	global_load_dwordx4 a[202:205], v[72:73], off offset:96
	global_load_dwordx4 a[210:213], v[68:69], off offset:96
	global_load_dwordx4 a[214:217], v[72:73], off offset:128
	global_load_dwordx4 a[218:221], v[68:69], off offset:128
	global_load_dwordx4 a[222:225], v[72:73], off offset:160
	global_load_dwordx4 a[226:229], v[68:69], off offset:160
	global_load_dwordx4 a[230:233], v[72:73], off offset:192
	global_load_dwordx4 a[234:237], v[68:69], off offset:192
	global_load_dwordx4 a[238:241], v[72:73], off offset:224
	global_load_dwordx4 a[242:245], v[68:69], off offset:224
	v_pk_mul_f32 v[16:17], v[14:15], v[66:67]
	v_accvgpr_write_b32 a8, v20
	v_pk_fma_f32 v[16:17], v[78:79], v[18:19], v[16:17] neg_lo:[0,0,1] neg_hi:[0,0,1]
	v_accvgpr_write_b32 a9, v21
	v_pk_mul_f32 v[22:23], v[50:51], v[16:17] op_sel_hi:[0,1]
	v_pk_mul_f32 v[16:17], v[78:79], v[66:67]
	v_accvgpr_write_b32 a22, v24
	v_pk_fma_f32 v[14:15], v[14:15], v[18:19], v[16:17]
	v_cvt_pk_bf16_f32 v16, v20, v21
	v_pk_mul_f32 v[18:19], v[50:51], v[14:15] op_sel_hi:[0,1]
	v_cvt_pk_bf16_f32 v14, v24, v25
	v_cvt_pk_bf16_f32 v15, v22, v23
	v_cvt_pk_bf16_f32 v17, v18, v19
	v_accvgpr_write_b32 a6, v18
	ds_write2_b64 v75, v[14:15], v[16:17] offset0:2 offset1:34
	v_accvgpr_write_b32 a7, v19
	v_accvgpr_write_b32 a23, v25
	v_accvgpr_write_b32 a20, v22
	v_accvgpr_write_b32 a21, v23
	s_waitcnt vmcnt(10)
	s_nop 1
	v_accvgpr_read_b32 v18, a194
	v_accvgpr_read_b32 v19, a195
	v_accvgpr_read_b32 v20, a196
	v_accvgpr_read_b32 v21, a197
	v_accvgpr_read_b32 v30, a198
	v_accvgpr_read_b32 v31, a199
	v_accvgpr_read_b32 v32, a200
	v_accvgpr_read_b32 v33, a201
	v_pk_mul_f32 v[14:15], v[6:7], v[30:31]
	s_nop 0
	v_pk_fma_f32 v[14:15], v[80:81], v[18:19], v[14:15] neg_lo:[0,0,1] neg_hi:[0,0,1]
	s_nop 0
	v_pk_mul_f32 v[24:25], v[50:51], v[14:15] op_sel_hi:[0,1]
	v_pk_mul_f32 v[14:15], v[80:81], v[30:31]
	s_nop 0
	v_pk_fma_f32 v[6:7], v[6:7], v[18:19], v[14:15]
	s_nop 0
	v_pk_mul_f32 v[16:17], v[50:51], v[6:7] op_sel_hi:[0,1]
	v_pk_mul_f32 v[6:7], v[0:1], v[32:33]
	v_accvgpr_write_b32 a19, v17
	v_pk_fma_f32 v[6:7], v[252:253], v[20:21], v[6:7] neg_lo:[0,0,1] neg_hi:[0,0,1]
	v_accvgpr_write_b32 a18, v16
	v_pk_mul_f32 v[26:27], v[50:51], v[6:7] op_sel_hi:[0,1]
	v_pk_mul_f32 v[6:7], v[252:253], v[32:33]
	s_nop 0
	v_pk_fma_f32 v[0:1], v[0:1], v[20:21], v[6:7]
	v_cvt_pk_bf16_f32 v6, v16, v17
	v_pk_mul_f32 v[14:15], v[50:51], v[0:1] op_sel_hi:[0,1]
	v_cvt_pk_bf16_f32 v0, v24, v25
	v_cvt_pk_bf16_f32 v1, v26, v27
	v_cvt_pk_bf16_f32 v7, v14, v15
	ds_write2_b64 v75, v[0:1], v[6:7] offset0:4 offset1:36
	v_accvgpr_write_b32 a10, v14
	v_accvgpr_write_b32 a11, v15
	s_waitcnt vmcnt(8)
	s_nop 1
	v_accvgpr_read_b32 v18, a202
	v_accvgpr_read_b32 v19, a203
	v_accvgpr_read_b32 v20, a204
	v_accvgpr_read_b32 v21, a205
	v_accvgpr_read_b32 v40, a210
	v_accvgpr_read_b32 v41, a211
	v_accvgpr_read_b32 v42, a212
	v_accvgpr_read_b32 v43, a213
	v_pk_mul_f32 v[0:1], v[2:3], v[40:41]
	s_nop 0
	v_pk_fma_f32 v[0:1], v[228:229], v[18:19], v[0:1] neg_lo:[0,0,1] neg_hi:[0,0,1]
	s_nop 0
	v_pk_mul_f32 v[32:33], v[50:51], v[0:1] op_sel_hi:[0,1]
	v_pk_mul_f32 v[0:1], v[228:229], v[40:41]
	s_nop 0
	v_pk_fma_f32 v[0:1], v[2:3], v[18:19], v[0:1]
	s_nop 0
	v_pk_mul_f32 v[22:23], v[50:51], v[0:1] op_sel_hi:[0,1]
	v_pk_mul_f32 v[0:1], v[76:77], v[42:43]
	v_cvt_pk_bf16_f32 v2, v22, v23
	v_pk_fma_f32 v[0:1], v[226:227], v[20:21], v[0:1] neg_lo:[0,0,1] neg_hi:[0,0,1]
	v_accvgpr_read_b32 v14, a208
	v_pk_mul_f32 v[34:35], v[50:51], v[0:1] op_sel_hi:[0,1]
	v_pk_mul_f32 v[0:1], v[226:227], v[42:43]
	v_accvgpr_read_b32 v15, a209
	v_pk_fma_f32 v[0:1], v[76:77], v[20:21], v[0:1]
	s_nop 0
	v_pk_mul_f32 v[6:7], v[50:51], v[0:1] op_sel_hi:[0,1]
	v_cvt_pk_bf16_f32 v0, v32, v33
	v_cvt_pk_bf16_f32 v1, v34, v35
	v_cvt_pk_bf16_f32 v3, v6, v7
	ds_write2_b64 v75, v[0:1], v[2:3] offset0:6 offset1:38
	v_accvgpr_write_b32 a25, v7
	v_accvgpr_write_b32 a24, v6
	v_accvgpr_read_b32 v6, a192
	v_accvgpr_read_b32 v7, a193
	s_waitcnt vmcnt(6)
	s_nop 1
	v_accvgpr_read_b32 v0, a214
	v_accvgpr_read_b32 v1, a215
	v_accvgpr_read_b32 v2, a216
	v_accvgpr_read_b32 v3, a217
	v_accvgpr_read_b32 v52, a218
	v_accvgpr_read_b32 v53, a219
	v_accvgpr_read_b32 v54, a220
	v_accvgpr_read_b32 v55, a221
	v_pk_mul_f32 v[16:17], v[14:15], v[52:53]
	s_nop 0
	v_pk_fma_f32 v[16:17], v[6:7], v[0:1], v[16:17] neg_lo:[0,0,1] neg_hi:[0,0,1]
	v_pk_mul_f32 v[6:7], v[6:7], v[52:53]
	v_pk_mul_f32 v[40:41], v[50:51], v[16:17] op_sel_hi:[0,1]
	v_pk_fma_f32 v[0:1], v[14:15], v[0:1], v[6:7]
	s_nop 0
	v_pk_mul_f32 v[30:31], v[50:51], v[0:1] op_sel_hi:[0,1]
	v_pk_mul_f32 v[0:1], v[28:29], v[54:55]
	s_nop 0
	v_pk_fma_f32 v[0:1], v[234:235], v[2:3], v[0:1] neg_lo:[0,0,1] neg_hi:[0,0,1]
	s_nop 0
	v_pk_mul_f32 v[42:43], v[50:51], v[0:1] op_sel_hi:[0,1]
	v_pk_mul_f32 v[0:1], v[234:235], v[54:55]
	s_nop 0
	v_pk_fma_f32 v[0:1], v[28:29], v[2:3], v[0:1]
	v_cvt_pk_bf16_f32 v2, v30, v31
	v_pk_mul_f32 v[28:29], v[50:51], v[0:1] op_sel_hi:[0,1]
	v_cvt_pk_bf16_f32 v0, v40, v41
	v_cvt_pk_bf16_f32 v1, v42, v43
	v_cvt_pk_bf16_f32 v3, v28, v29
	ds_write2_b64 v75, v[0:1], v[2:3] offset0:8 offset1:40
	s_waitcnt vmcnt(4)
	s_nop 1
	v_accvgpr_read_b32 v0, a222
	v_accvgpr_read_b32 v1, a223
	v_accvgpr_read_b32 v2, a224
	v_accvgpr_read_b32 v3, a225
	v_accvgpr_read_b32 v52, a226
	v_accvgpr_read_b32 v53, a227
	v_accvgpr_read_b32 v54, a228
	v_accvgpr_read_b32 v55, a229
	v_pk_mul_f32 v[6:7], v[38:39], v[52:53]
	s_nop 0
	v_pk_fma_f32 v[6:7], v[210:211], v[0:1], v[6:7] neg_lo:[0,0,1] neg_hi:[0,0,1]
	s_nop 0
	v_pk_mul_f32 v[58:59], v[50:51], v[6:7] op_sel_hi:[0,1]
	v_pk_mul_f32 v[6:7], v[210:211], v[52:53]
	s_nop 0
	v_pk_fma_f32 v[0:1], v[38:39], v[0:1], v[6:7]
	s_nop 0
	v_pk_mul_f32 v[38:39], v[50:51], v[0:1] op_sel_hi:[0,1]
	v_pk_mul_f32 v[0:1], v[36:37], v[54:55]
	s_nop 0
	v_pk_fma_f32 v[0:1], v[100:101], v[2:3], v[0:1] neg_lo:[0,0,1] neg_hi:[0,0,1]
	s_nop 0
	v_pk_mul_f32 v[14:15], v[50:51], v[0:1] op_sel_hi:[0,1]
	v_pk_mul_f32 v[0:1], v[100:101], v[54:55]
	s_nop 0
	v_pk_fma_f32 v[0:1], v[36:37], v[2:3], v[0:1]
	v_cvt_pk_bf16_f32 v2, v38, v39
	v_pk_mul_f32 v[36:37], v[50:51], v[0:1] op_sel_hi:[0,1]
	v_cvt_pk_bf16_f32 v0, v58, v59
	v_cvt_pk_bf16_f32 v1, v14, v15
	v_cvt_pk_bf16_f32 v3, v36, v37
	ds_write2_b64 v75, v[0:1], v[2:3] offset0:10 offset1:42
	s_waitcnt vmcnt(2)
	s_nop 1
	v_accvgpr_read_b32 v0, a230
	v_accvgpr_read_b32 v1, a231
	v_accvgpr_read_b32 v2, a232
	v_accvgpr_read_b32 v3, a233
	v_accvgpr_read_b32 v64, a234
	v_accvgpr_read_b32 v65, a235
	v_accvgpr_read_b32 v66, a236
	v_accvgpr_read_b32 v67, a237
	v_pk_mul_f32 v[6:7], v[62:63], v[64:65]
	s_nop 0
	v_pk_fma_f32 v[6:7], v[104:105], v[0:1], v[6:7] neg_lo:[0,0,1] neg_hi:[0,0,1]
	s_nop 0
	v_pk_mul_f32 v[100:101], v[50:51], v[6:7] op_sel_hi:[0,1]
	v_pk_mul_f32 v[6:7], v[104:105], v[64:65]
	s_nop 0
	v_pk_fma_f32 v[0:1], v[62:63], v[0:1], v[6:7]
	s_nop 0
	v_pk_mul_f32 v[54:55], v[50:51], v[0:1] op_sel_hi:[0,1]
	v_pk_mul_f32 v[0:1], v[48:49], v[66:67]
	s_nop 0
	v_pk_fma_f32 v[0:1], v[114:115], v[2:3], v[0:1] neg_lo:[0,0,1] neg_hi:[0,0,1]
	s_nop 0
	v_pk_mul_f32 v[104:105], v[50:51], v[0:1] op_sel_hi:[0,1]
	v_pk_mul_f32 v[0:1], v[114:115], v[66:67]
	s_nop 0
	v_pk_fma_f32 v[0:1], v[48:49], v[2:3], v[0:1]
	v_cvt_pk_bf16_f32 v2, v54, v55
	v_pk_mul_f32 v[52:53], v[50:51], v[0:1] op_sel_hi:[0,1]
	v_cvt_pk_bf16_f32 v0, v100, v101
	v_cvt_pk_bf16_f32 v1, v104, v105
	v_cvt_pk_bf16_f32 v3, v52, v53
	ds_write2_b64 v75, v[0:1], v[2:3] offset0:12 offset1:44
	s_waitcnt vmcnt(0)
	s_nop 1
	v_accvgpr_read_b32 v0, a238
	v_accvgpr_read_b32 v1, a239
	v_accvgpr_read_b32 v2, a240
	v_accvgpr_read_b32 v3, a241
	v_accvgpr_read_b32 v64, a242
	v_accvgpr_read_b32 v65, a243
	v_accvgpr_read_b32 v66, a244
	v_accvgpr_read_b32 v67, a245
	v_pk_mul_f32 v[6:7], v[60:61], v[64:65]
	s_nop 0
	v_pk_fma_f32 v[6:7], v[118:119], v[0:1], v[6:7] neg_lo:[0,0,1] neg_hi:[0,0,1]
	s_nop 0
	v_pk_mul_f32 v[114:115], v[50:51], v[6:7] op_sel_hi:[0,1]
	v_pk_mul_f32 v[6:7], v[118:119], v[64:65]
	s_nop 0
	v_pk_fma_f32 v[0:1], v[60:61], v[0:1], v[6:7]
	s_nop 0
	v_pk_mul_f32 v[64:65], v[50:51], v[0:1] op_sel_hi:[0,1]
	v_pk_mul_f32 v[0:1], v[44:45], v[66:67]
	s_nop 0
	v_pk_fma_f32 v[0:1], v[168:169], v[2:3], v[0:1] neg_lo:[0,0,1] neg_hi:[0,0,1]
	s_nop 0
	v_pk_mul_f32 v[118:119], v[50:51], v[0:1] op_sel_hi:[0,1]
	v_pk_mul_f32 v[0:1], v[168:169], v[66:67]
	s_nop 0
	v_pk_fma_f32 v[0:1], v[44:45], v[2:3], v[0:1]
	v_cvt_pk_bf16_f32 v2, v64, v65
	v_pk_mul_f32 v[66:67], v[50:51], v[0:1] op_sel_hi:[0,1]
	v_cvt_pk_bf16_f32 v0, v114, v115
	v_cvt_pk_bf16_f32 v1, v118, v119
	v_cvt_pk_bf16_f32 v3, v66, v67
	ds_write2_b64 v75, v[0:1], v[2:3] offset0:14 offset1:46
	v_or_b32_e32 v60, 32, v74
	v_or_b32_e32 v0, s66, v60
	v_lshlrev_b32_e32 v94, 9, v0
	v_lshl_add_u64 v[76:77], v[184:185], 0, v[94:95]
	v_lshl_add_u64 v[6:7], v[186:187], 0, v[94:95]
	global_load_dwordx4 a[192:195], v[76:77], off
	global_load_dwordx4 a[196:199], v[6:7], off
	global_load_dwordx4 a[200:203], v[76:77], off offset:32
	global_load_dwordx4 a[204:207], v[6:7], off offset:32
	global_load_dwordx4 a[208:211], v[76:77], off offset:64
	global_load_dwordx4 a[212:215], v[6:7], off offset:64
	global_load_dwordx4 a[216:219], v[76:77], off offset:96
	global_load_dwordx4 a[220:223], v[6:7], off offset:96
	global_load_dwordx4 a[224:227], v[76:77], off offset:128
	global_load_dwordx4 a[228:231], v[6:7], off offset:128
	global_load_dwordx4 a[232:235], v[76:77], off offset:160
	global_load_dwordx4 a[236:239], v[6:7], off offset:160
	global_load_dwordx4 a[240:243], v[76:77], off offset:192
	global_load_dwordx4 a[244:247], v[6:7], off offset:192
	global_load_dwordx4 a[248:251], v[76:77], off offset:224
	global_load_dwordx4 a[252:255], v[6:7], off offset:224
	v_accvgpr_read_b32 v18, a176
	v_accvgpr_read_b32 v16, a160
	v_accvgpr_read_b32 v19, a177
	v_accvgpr_read_b32 v17, a161
	s_waitcnt vmcnt(14)
	s_nop 1
	v_accvgpr_read_b32 v0, a192
	v_accvgpr_read_b32 v1, a193
	v_accvgpr_read_b32 v2, a194
	v_accvgpr_read_b32 v3, a195
	v_accvgpr_read_b32 v78, a196
	v_accvgpr_read_b32 v79, a197
	v_accvgpr_read_b32 v80, a198
	v_accvgpr_read_b32 v81, a199
	v_pk_mul_f32 v[44:45], v[18:19], v[78:79]
	s_nop 0
	v_pk_fma_f32 v[44:45], v[16:17], v[0:1], v[44:45] neg_lo:[0,0,1] neg_hi:[0,0,1]
	v_pk_mul_f32 v[16:17], v[16:17], v[78:79]
	v_pk_mul_f32 v[68:69], v[50:51], v[44:45] op_sel_hi:[0,1]
	v_pk_fma_f32 v[0:1], v[18:19], v[0:1], v[16:17]
	s_nop 0
	v_pk_mul_f32 v[48:49], v[50:51], v[0:1] op_sel_hi:[0,1]
	v_pk_mul_f32 v[0:1], v[70:71], v[80:81]
	v_cvt_pk_bf16_f32 v16, v48, v49
	v_pk_fma_f32 v[0:1], v[108:109], v[2:3], v[0:1] neg_lo:[0,0,1] neg_hi:[0,0,1]
	s_nop 0
	v_pk_mul_f32 v[62:63], v[50:51], v[0:1] op_sel_hi:[0,1]
	v_pk_mul_f32 v[0:1], v[108:109], v[80:81]
	s_nop 0
	v_pk_fma_f32 v[0:1], v[70:71], v[2:3], v[0:1]
	v_cvt_pk_bf16_f32 v2, v68, v69
	v_pk_mul_f32 v[44:45], v[50:51], v[0:1] op_sel_hi:[0,1]
	v_cvt_pk_bf16_f32 v3, v62, v63
	v_cvt_pk_bf16_f32 v17, v44, v45
	v_mad_u32_u24 v0, v60, s25, v51
	ds_write2_b64 v0, v[2:3], v[16:17] offset1:32
	s_waitcnt vmcnt(12)
	s_nop 1
	v_accvgpr_read_b32 v78, a200
	v_accvgpr_read_b32 v79, a201
	v_accvgpr_read_b32 v80, a202
	v_accvgpr_read_b32 v81, a203
	v_accvgpr_read_b32 v226, a204
	v_accvgpr_read_b32 v227, a205
	v_accvgpr_read_b32 v228, a206
	v_accvgpr_read_b32 v229, a207
	v_pk_mul_f32 v[2:3], v[206:207], v[226:227]
	s_nop 0
	v_pk_fma_f32 v[2:3], v[120:121], v[78:79], v[2:3] neg_lo:[0,0,1] neg_hi:[0,0,1]
	s_nop 0
	v_pk_mul_f32 v[108:109], v[50:51], v[2:3] op_sel_hi:[0,1]
	v_pk_mul_f32 v[2:3], v[120:121], v[226:227]
	s_nop 0
	v_pk_fma_f32 v[2:3], v[206:207], v[78:79], v[2:3]
	s_nop 0
	v_pk_mul_f32 v[72:73], v[50:51], v[2:3] op_sel_hi:[0,1]
	v_pk_mul_f32 v[2:3], v[164:165], v[228:229]
	v_cvt_pk_bf16_f32 v16, v72, v73
	v_pk_fma_f32 v[2:3], v[134:135], v[80:81], v[2:3] neg_lo:[0,0,1] neg_hi:[0,0,1]
	s_nop 0
	v_pk_mul_f32 v[120:121], v[50:51], v[2:3] op_sel_hi:[0,1]
	v_pk_mul_f32 v[2:3], v[134:135], v[228:229]
	s_nop 0
	v_pk_fma_f32 v[2:3], v[164:165], v[80:81], v[2:3]
	s_nop 0
	v_pk_mul_f32 v[70:71], v[50:51], v[2:3] op_sel_hi:[0,1]
	v_cvt_pk_bf16_f32 v2, v108, v109
	v_cvt_pk_bf16_f32 v3, v120, v121
	v_cvt_pk_bf16_f32 v17, v70, v71
	ds_write2_b64 v0, v[2:3], v[16:17] offset0:2 offset1:34
	s_waitcnt vmcnt(10)
	s_nop 1
	v_accvgpr_read_b32 v78, a208
	v_accvgpr_read_b32 v79, a209
	v_accvgpr_read_b32 v80, a210
	v_accvgpr_read_b32 v81, a211
	v_accvgpr_read_b32 v226, a212
	v_accvgpr_read_b32 v227, a213
	v_accvgpr_read_b32 v228, a214
	v_accvgpr_read_b32 v229, a215
	v_pk_mul_f32 v[2:3], v[136:137], v[226:227]
	s_nop 0
	v_pk_fma_f32 v[2:3], v[112:113], v[78:79], v[2:3] neg_lo:[0,0,1] neg_hi:[0,0,1]
	s_nop 0
	v_pk_mul_f32 v[134:135], v[50:51], v[2:3] op_sel_hi:[0,1]
	v_pk_mul_f32 v[2:3], v[112:113], v[226:227]
	s_nop 0
	v_pk_fma_f32 v[2:3], v[136:137], v[78:79], v[2:3]
	s_nop 0
	v_pk_mul_f32 v[112:113], v[50:51], v[2:3] op_sel_hi:[0,1]
	v_pk_mul_f32 v[2:3], v[152:153], v[228:229]
	v_cvt_pk_bf16_f32 v16, v112, v113
	v_pk_fma_f32 v[2:3], v[110:111], v[80:81], v[2:3] neg_lo:[0,0,1] neg_hi:[0,0,1]
	s_nop 0
	v_pk_mul_f32 v[136:137], v[50:51], v[2:3] op_sel_hi:[0,1]
	v_pk_mul_f32 v[2:3], v[110:111], v[228:229]
	s_nop 0
	v_pk_fma_f32 v[2:3], v[152:153], v[80:81], v[2:3]
	s_nop 0
	v_pk_mul_f32 v[110:111], v[50:51], v[2:3] op_sel_hi:[0,1]
	v_cvt_pk_bf16_f32 v2, v134, v135
	v_cvt_pk_bf16_f32 v3, v136, v137
	v_cvt_pk_bf16_f32 v17, v110, v111
	ds_write2_b64 v0, v[2:3], v[16:17] offset0:4 offset1:36
	s_waitcnt vmcnt(8)
	s_nop 1
	v_accvgpr_read_b32 v78, a216
	v_accvgpr_read_b32 v79, a217
	v_accvgpr_read_b32 v80, a218
	v_accvgpr_read_b32 v81, a219
	v_accvgpr_read_b32 v226, a220
	v_accvgpr_read_b32 v227, a221
	v_accvgpr_read_b32 v228, a222
	v_accvgpr_read_b32 v229, a223
	v_pk_mul_f32 v[2:3], v[154:155], v[226:227]
	s_nop 0
	v_pk_fma_f32 v[2:3], v[132:133], v[78:79], v[2:3] neg_lo:[0,0,1] neg_hi:[0,0,1]
	s_nop 0
	v_pk_mul_f32 v[152:153], v[50:51], v[2:3] op_sel_hi:[0,1]
	v_pk_mul_f32 v[2:3], v[132:133], v[226:227]
	s_nop 0
	v_pk_fma_f32 v[2:3], v[154:155], v[78:79], v[2:3]
	s_nop 0
	v_pk_mul_f32 v[132:133], v[50:51], v[2:3] op_sel_hi:[0,1]
	v_pk_mul_f32 v[2:3], v[146:147], v[228:229]
	v_cvt_pk_bf16_f32 v16, v132, v133
	v_pk_fma_f32 v[2:3], v[130:131], v[80:81], v[2:3] neg_lo:[0,0,1] neg_hi:[0,0,1]
	s_nop 0
	v_pk_mul_f32 v[154:155], v[50:51], v[2:3] op_sel_hi:[0,1]
	v_pk_mul_f32 v[2:3], v[130:131], v[228:229]
	s_nop 0
	v_pk_fma_f32 v[2:3], v[146:147], v[80:81], v[2:3]
	s_nop 0
	v_pk_mul_f32 v[130:131], v[50:51], v[2:3] op_sel_hi:[0,1]
	v_cvt_pk_bf16_f32 v2, v152, v153
	v_cvt_pk_bf16_f32 v3, v154, v155
	v_cvt_pk_bf16_f32 v17, v130, v131
	ds_write2_b64 v0, v[2:3], v[16:17] offset0:6 offset1:38
	v_accvgpr_read_b32 v16, a144
	v_accvgpr_read_b32 v2, a128
	v_accvgpr_read_b32 v17, a145
	v_accvgpr_read_b32 v3, a129
	s_waitcnt vmcnt(6)
	s_nop 1
	v_accvgpr_read_b32 v78, a224
	v_accvgpr_read_b32 v79, a225
	v_accvgpr_read_b32 v80, a226
	v_accvgpr_read_b32 v81, a227
	v_accvgpr_read_b32 v226, a228
	v_accvgpr_read_b32 v227, a229
	v_accvgpr_read_b32 v228, a230
	v_accvgpr_read_b32 v229, a231
	v_pk_mul_f32 v[18:19], v[16:17], v[226:227]
	s_nop 0
	v_pk_fma_f32 v[18:19], v[2:3], v[78:79], v[18:19] neg_lo:[0,0,1] neg_hi:[0,0,1]
	v_pk_mul_f32 v[2:3], v[2:3], v[226:227]
	v_pk_mul_f32 v[164:165], v[50:51], v[18:19] op_sel_hi:[0,1]
	v_pk_fma_f32 v[2:3], v[16:17], v[78:79], v[2:3]
	s_nop 0
	v_pk_mul_f32 v[146:147], v[50:51], v[2:3] op_sel_hi:[0,1]
	v_pk_mul_f32 v[2:3], v[180:181], v[228:229]
	v_cvt_pk_bf16_f32 v16, v146, v147
	v_pk_fma_f32 v[2:3], v[144:145], v[80:81], v[2:3] neg_lo:[0,0,1] neg_hi:[0,0,1]
	s_nop 0
	v_pk_mul_f32 v[168:169], v[50:51], v[2:3] op_sel_hi:[0,1]
	v_pk_mul_f32 v[2:3], v[144:145], v[228:229]
	s_nop 0
	v_pk_fma_f32 v[2:3], v[180:181], v[80:81], v[2:3]
	s_nop 0
	v_pk_mul_f32 v[144:145], v[50:51], v[2:3] op_sel_hi:[0,1]
	v_cvt_pk_bf16_f32 v2, v164, v165
	v_cvt_pk_bf16_f32 v3, v168, v169
	v_cvt_pk_bf16_f32 v17, v144, v145
	ds_write2_b64 v0, v[2:3], v[16:17] offset0:8 offset1:40
	s_waitcnt vmcnt(4)
	s_nop 1
	v_accvgpr_read_b32 v78, a232
	v_accvgpr_read_b32 v79, a233
	v_accvgpr_read_b32 v80, a234
	v_accvgpr_read_b32 v81, a235
	v_accvgpr_read_b32 v226, a236
	v_accvgpr_read_b32 v227, a237
	v_accvgpr_read_b32 v228, a238
	v_accvgpr_read_b32 v229, a239
	v_pk_mul_f32 v[2:3], v[182:183], v[226:227]
	s_nop 0
	v_pk_fma_f32 v[2:3], v[158:159], v[78:79], v[2:3] neg_lo:[0,0,1] neg_hi:[0,0,1]
	s_nop 0
	v_pk_mul_f32 v[180:181], v[50:51], v[2:3] op_sel_hi:[0,1]
	v_pk_mul_f32 v[2:3], v[158:159], v[226:227]
	s_nop 0
	v_pk_fma_f32 v[2:3], v[182:183], v[78:79], v[2:3]
	s_nop 0
	v_pk_mul_f32 v[158:159], v[50:51], v[2:3] op_sel_hi:[0,1]
	v_pk_mul_f32 v[2:3], v[200:201], v[228:229]
	v_cvt_pk_bf16_f32 v16, v158, v159
	v_pk_fma_f32 v[2:3], v[156:157], v[80:81], v[2:3] neg_lo:[0,0,1] neg_hi:[0,0,1]
	s_nop 0
	v_pk_mul_f32 v[182:183], v[50:51], v[2:3] op_sel_hi:[0,1]
	v_pk_mul_f32 v[2:3], v[156:157], v[228:229]
	s_nop 0
	v_pk_fma_f32 v[2:3], v[200:201], v[80:81], v[2:3]
	s_nop 0
	v_pk_mul_f32 v[156:157], v[50:51], v[2:3] op_sel_hi:[0,1]
	v_cvt_pk_bf16_f32 v2, v180, v181
	v_cvt_pk_bf16_f32 v3, v182, v183
	v_cvt_pk_bf16_f32 v17, v156, v157
	ds_write2_b64 v0, v[2:3], v[16:17] offset0:10 offset1:42
	s_waitcnt vmcnt(2)
	s_nop 1
	v_accvgpr_read_b32 v78, a240
	v_accvgpr_read_b32 v79, a241
	v_accvgpr_read_b32 v80, a242
	v_accvgpr_read_b32 v81, a243
	v_accvgpr_read_b32 v226, a244
	v_accvgpr_read_b32 v227, a245
	v_accvgpr_read_b32 v228, a246
	v_accvgpr_read_b32 v229, a247
	v_pk_mul_f32 v[2:3], v[198:199], v[226:227]
	s_nop 0
	v_pk_fma_f32 v[2:3], v[178:179], v[78:79], v[2:3] neg_lo:[0,0,1] neg_hi:[0,0,1]
	s_nop 0
	v_pk_mul_f32 v[206:207], v[50:51], v[2:3] op_sel_hi:[0,1]
	v_pk_mul_f32 v[2:3], v[178:179], v[226:227]
	s_nop 0
	v_pk_fma_f32 v[2:3], v[198:199], v[78:79], v[2:3]
	s_nop 0
	v_pk_mul_f32 v[178:179], v[50:51], v[2:3] op_sel_hi:[0,1]
	v_pk_mul_f32 v[2:3], v[4:5], v[228:229]
	s_nop 0
	v_pk_fma_f32 v[2:3], v[176:177], v[80:81], v[2:3] neg_lo:[0,0,1] neg_hi:[0,0,1]
	s_nop 0
	v_pk_mul_f32 v[210:211], v[50:51], v[2:3] op_sel_hi:[0,1]
	v_pk_mul_f32 v[2:3], v[176:177], v[228:229]
	s_nop 0
	v_pk_fma_f32 v[2:3], v[4:5], v[80:81], v[2:3]
	v_cvt_pk_bf16_f32 v4, v178, v179
	v_pk_mul_f32 v[176:177], v[50:51], v[2:3] op_sel_hi:[0,1]
	v_cvt_pk_bf16_f32 v2, v206, v207
	v_cvt_pk_bf16_f32 v3, v210, v211
	v_cvt_pk_bf16_f32 v5, v176, v177
	ds_write2_b64 v0, v[2:3], v[4:5] offset0:12 offset1:44
	s_nop 0
	s_waitcnt vmcnt(0)
	s_nop 1
	v_accvgpr_read_b32 v2, a248
	v_accvgpr_read_b32 v3, a249
	v_accvgpr_read_b32 v4, a250
	v_accvgpr_read_b32 v5, a251
	v_accvgpr_read_b32 v76, a252
	v_accvgpr_read_b32 v77, a253
	v_accvgpr_read_b32 v78, a254
	v_accvgpr_read_b32 v79, a255
	v_pk_mul_f32 v[6:7], v[196:197], v[76:77]
	s_nop 0
	v_pk_fma_f32 v[6:7], v[194:195], v[2:3], v[6:7] neg_lo:[0,0,1] neg_hi:[0,0,1]
	s_nop 0
	v_pk_mul_f32 v[226:227], v[50:51], v[6:7] op_sel_hi:[0,1]
	v_pk_mul_f32 v[6:7], v[194:195], v[76:77]
	s_nop 0
	v_pk_fma_f32 v[2:3], v[196:197], v[2:3], v[6:7]
	s_nop 0
	v_pk_mul_f32 v[196:197], v[50:51], v[2:3] op_sel_hi:[0,1]
	v_pk_mul_f32 v[2:3], v[12:13], v[78:79]
	s_nop 0
	v_pk_fma_f32 v[2:3], v[174:175], v[4:5], v[2:3] neg_lo:[0,0,1] neg_hi:[0,0,1]
	s_nop 0
	v_pk_mul_f32 v[228:229], v[50:51], v[2:3] op_sel_hi:[0,1]
	v_pk_mul_f32 v[2:3], v[174:175], v[78:79]
	s_nop 0
	v_pk_fma_f32 v[2:3], v[12:13], v[4:5], v[2:3]
	v_cvt_pk_bf16_f32 v4, v196, v197
	v_pk_mul_f32 v[198:199], v[50:51], v[2:3] op_sel_hi:[0,1]
	v_cvt_pk_bf16_f32 v2, v226, v227
	v_cvt_pk_bf16_f32 v3, v228, v229
	v_cvt_pk_bf16_f32 v5, v198, v199
	ds_write2_b64 v0, v[2:3], v[4:5] offset0:14 offset1:46
	v_or_b32_e32 v60, 64, v74
	v_or_b32_e32 v0, s66, v60
	v_lshlrev_b32_e32 v94, 9, v0
	v_lshl_add_u64 v[6:7], v[184:185], 0, v[94:95]
	v_lshl_add_u64 v[4:5], v[186:187], 0, v[94:95]
	global_load_dwordx4 a[192:195], v[6:7], off
	global_load_dwordx4 a[196:199], v[4:5], off
	global_load_dwordx4 a[200:203], v[6:7], off offset:32
	global_load_dwordx4 a[204:207], v[4:5], off offset:32
	global_load_dwordx4 a[208:211], v[6:7], off offset:64
	global_load_dwordx4 a[212:215], v[4:5], off offset:64
	global_load_dwordx4 a[216:219], v[6:7], off offset:96
	global_load_dwordx4 a[220:223], v[4:5], off offset:96
	global_load_dwordx4 a[224:227], v[6:7], off offset:128
	global_load_dwordx4 a[228:231], v[4:5], off offset:128
	global_load_dwordx4 a[232:235], v[6:7], off offset:160
	global_load_dwordx4 a[236:239], v[4:5], off offset:160
	global_load_dwordx4 a[240:243], v[6:7], off offset:192
	global_load_dwordx4 a[244:247], v[4:5], off offset:192
	global_load_dwordx4 a[248:251], v[6:7], off offset:224
	global_load_dwordx4 a[252:255], v[4:5], off offset:224
	v_accvgpr_read_b32 v16, a112
	v_accvgpr_read_b32 v12, a96
	v_accvgpr_read_b32 v17, a113
	v_accvgpr_read_b32 v13, a97
	s_waitcnt vmcnt(14)
	s_nop 1
	v_accvgpr_read_b32 v0, a192
	v_accvgpr_read_b32 v1, a193
	v_accvgpr_read_b32 v2, a194
	v_accvgpr_read_b32 v3, a195
	v_accvgpr_read_b32 v76, a196
	v_accvgpr_read_b32 v77, a197
	v_accvgpr_read_b32 v78, a198
	v_accvgpr_read_b32 v79, a199
	v_pk_mul_f32 v[18:19], v[16:17], v[76:77]
	s_nop 0
	v_pk_fma_f32 v[18:19], v[12:13], v[0:1], v[18:19] neg_lo:[0,0,1] neg_hi:[0,0,1]
	v_pk_mul_f32 v[12:13], v[12:13], v[76:77]
	v_pk_mul_f32 v[200:201], v[50:51], v[18:19] op_sel_hi:[0,1]
	v_pk_fma_f32 v[0:1], v[16:17], v[0:1], v[12:13]
	v_mad_u32_u24 v12, v60, s25, v51
	v_pk_mul_f32 v[174:175], v[50:51], v[0:1] op_sel_hi:[0,1]
	v_pk_mul_f32 v[0:1], v[216:217], v[78:79]
	s_nop 0
	v_pk_fma_f32 v[0:1], v[172:173], v[2:3], v[0:1] neg_lo:[0,0,1] neg_hi:[0,0,1]
	s_nop 0
	v_pk_mul_f32 v[194:195], v[50:51], v[0:1] op_sel_hi:[0,1]
	v_pk_mul_f32 v[0:1], v[172:173], v[78:79]
	s_nop 0
	v_pk_fma_f32 v[0:1], v[216:217], v[2:3], v[0:1]
	v_cvt_pk_bf16_f32 v2, v174, v175
	v_pk_mul_f32 v[172:173], v[50:51], v[0:1] op_sel_hi:[0,1]
	v_cvt_pk_bf16_f32 v0, v200, v201
	v_cvt_pk_bf16_f32 v1, v194, v195
	v_cvt_pk_bf16_f32 v3, v172, v173
	ds_write2_b64 v12, v[0:1], v[2:3] offset1:32
	s_waitcnt vmcnt(12)
	s_nop 1
	v_accvgpr_read_b32 v0, a200
	v_accvgpr_read_b32 v1, a201
	v_accvgpr_read_b32 v2, a202
	v_accvgpr_read_b32 v3, a203
	v_accvgpr_read_b32 v76, a204
	v_accvgpr_read_b32 v77, a205
	v_accvgpr_read_b32 v78, a206
	v_accvgpr_read_b32 v79, a207
	v_pk_mul_f32 v[16:17], v[232:233], v[76:77]
	s_nop 0
	v_pk_fma_f32 v[16:17], v[204:205], v[0:1], v[16:17] neg_lo:[0,0,1] neg_hi:[0,0,1]
	s_nop 0
	v_pk_mul_f32 v[216:217], v[50:51], v[16:17] op_sel_hi:[0,1]
	v_pk_mul_f32 v[16:17], v[204:205], v[76:77]
	s_nop 0
	v_pk_fma_f32 v[0:1], v[232:233], v[0:1], v[16:17]
	s_nop 0
	v_pk_mul_f32 v[204:205], v[50:51], v[0:1] op_sel_hi:[0,1]
	v_pk_mul_f32 v[0:1], v[224:225], v[78:79]
	s_nop 0
	v_pk_fma_f32 v[0:1], v[202:203], v[2:3], v[0:1] neg_lo:[0,0,1] neg_hi:[0,0,1]
	s_nop 0
	v_pk_mul_f32 v[232:233], v[50:51], v[0:1] op_sel_hi:[0,1]
	v_pk_mul_f32 v[0:1], v[202:203], v[78:79]
	s_nop 0
	v_pk_fma_f32 v[0:1], v[224:225], v[2:3], v[0:1]
	v_cvt_pk_bf16_f32 v2, v204, v205
	v_pk_mul_f32 v[202:203], v[50:51], v[0:1] op_sel_hi:[0,1]
	v_cvt_pk_bf16_f32 v0, v216, v217
	v_cvt_pk_bf16_f32 v1, v232, v233
	v_cvt_pk_bf16_f32 v3, v202, v203
	ds_write2_b64 v12, v[0:1], v[2:3] offset0:2 offset1:34
	s_waitcnt vmcnt(10)
	s_nop 1
	v_accvgpr_read_b32 v0, a208
	v_accvgpr_read_b32 v1, a209
	v_accvgpr_read_b32 v2, a210
	v_accvgpr_read_b32 v3, a211
	v_accvgpr_read_b32 v76, a212
	v_accvgpr_read_b32 v77, a213
	v_accvgpr_read_b32 v78, a214
	v_accvgpr_read_b32 v79, a215
	v_pk_mul_f32 v[16:17], v[236:237], v[76:77]
	s_nop 0
	v_pk_fma_f32 v[16:17], v[220:221], v[0:1], v[16:17] neg_lo:[0,0,1] neg_hi:[0,0,1]
	s_nop 0
	v_pk_mul_f32 v[234:235], v[50:51], v[16:17] op_sel_hi:[0,1]
	v_pk_mul_f32 v[16:17], v[220:221], v[76:77]
	s_nop 0
	v_pk_fma_f32 v[0:1], v[236:237], v[0:1], v[16:17]
	s_nop 0
	v_pk_mul_f32 v[220:221], v[50:51], v[0:1] op_sel_hi:[0,1]
	v_pk_mul_f32 v[0:1], v[246:247], v[78:79]
	s_nop 0
	v_pk_fma_f32 v[0:1], v[218:219], v[2:3], v[0:1] neg_lo:[0,0,1] neg_hi:[0,0,1]
	s_nop 0
	v_pk_mul_f32 v[236:237], v[50:51], v[0:1] op_sel_hi:[0,1]
	v_pk_mul_f32 v[0:1], v[218:219], v[78:79]
	s_nop 0
	v_pk_fma_f32 v[0:1], v[246:247], v[2:3], v[0:1]
	v_cvt_pk_bf16_f32 v2, v220, v221
	v_pk_mul_f32 v[218:219], v[50:51], v[0:1] op_sel_hi:[0,1]
	v_cvt_pk_bf16_f32 v0, v234, v235
	v_cvt_pk_bf16_f32 v1, v236, v237
	v_cvt_pk_bf16_f32 v3, v218, v219
	ds_write2_b64 v12, v[0:1], v[2:3] offset0:4 offset1:36
	s_waitcnt vmcnt(8)
	s_nop 1
	v_accvgpr_read_b32 v0, a216
	v_accvgpr_read_b32 v1, a217
	v_accvgpr_read_b32 v2, a218
	v_accvgpr_read_b32 v3, a219
	v_accvgpr_read_b32 v76, a220
	v_accvgpr_read_b32 v77, a221
	v_accvgpr_read_b32 v78, a222
	v_accvgpr_read_b32 v79, a223
	v_pk_mul_f32 v[16:17], v[244:245], v[76:77]
	s_nop 0
	v_pk_fma_f32 v[16:17], v[212:213], v[0:1], v[16:17] neg_lo:[0,0,1] neg_hi:[0,0,1]
	s_nop 0
	v_pk_mul_f32 v[246:247], v[50:51], v[16:17] op_sel_hi:[0,1]
	v_pk_mul_f32 v[16:17], v[212:213], v[76:77]
	s_nop 0
	v_pk_fma_f32 v[0:1], v[244:245], v[0:1], v[16:17]
	s_nop 0
	v_pk_mul_f32 v[212:213], v[50:51], v[0:1] op_sel_hi:[0,1]
	v_pk_mul_f32 v[0:1], v[242:243], v[78:79]
	v_accvgpr_read_b32 v18, a80
	v_pk_fma_f32 v[0:1], v[208:209], v[2:3], v[0:1] neg_lo:[0,0,1] neg_hi:[0,0,1]
	v_accvgpr_read_b32 v16, a64
	v_pk_mul_f32 v[244:245], v[50:51], v[0:1] op_sel_hi:[0,1]
	v_pk_mul_f32 v[0:1], v[208:209], v[78:79]
	v_accvgpr_read_b32 v19, a81
	v_pk_fma_f32 v[0:1], v[242:243], v[2:3], v[0:1]
	v_cvt_pk_bf16_f32 v2, v212, v213
	v_pk_mul_f32 v[208:209], v[50:51], v[0:1] op_sel_hi:[0,1]
	v_cvt_pk_bf16_f32 v0, v246, v247
	v_cvt_pk_bf16_f32 v1, v244, v245
	v_cvt_pk_bf16_f32 v3, v208, v209
	ds_write2_b64 v12, v[0:1], v[2:3] offset0:6 offset1:38
	v_accvgpr_read_b32 v17, a65
	s_waitcnt vmcnt(6)
	s_nop 1
	v_accvgpr_read_b32 v0, a224
	v_accvgpr_read_b32 v1, a225
	v_accvgpr_read_b32 v2, a226
	v_accvgpr_read_b32 v3, a227
	v_accvgpr_read_b32 v76, a228
	v_accvgpr_read_b32 v77, a229
	v_accvgpr_read_b32 v78, a230
	v_accvgpr_read_b32 v79, a231
	v_pk_mul_f32 v[60:61], v[18:19], v[76:77]
	s_nop 0
	v_pk_fma_f32 v[60:61], v[16:17], v[0:1], v[60:61] neg_lo:[0,0,1] neg_hi:[0,0,1]
	v_pk_mul_f32 v[16:17], v[16:17], v[76:77]
	v_pk_mul_f32 v[252:253], v[50:51], v[60:61] op_sel_hi:[0,1]
	v_pk_fma_f32 v[0:1], v[18:19], v[0:1], v[16:17]
	s_nop 0
	v_pk_mul_f32 v[242:243], v[50:51], v[0:1] op_sel_hi:[0,1]
	v_pk_mul_f32 v[0:1], v[10:11], v[78:79]
	v_pk_mul_f32 v[16:17], v[214:215], v[78:79]
	v_pk_fma_f32 v[0:1], v[214:215], v[2:3], v[0:1] neg_lo:[0,0,1] neg_hi:[0,0,1]
	v_pk_fma_f32 v[2:3], v[10:11], v[2:3], v[16:17]
	v_pk_mul_f32 v[0:1], v[50:51], v[0:1] op_sel_hi:[0,1]
	v_pk_mul_f32 v[214:215], v[50:51], v[2:3] op_sel_hi:[0,1]
	v_cvt_pk_bf16_f32 v2, v252, v253
	v_cvt_pk_bf16_f32 v3, v0, v1
	v_cvt_pk_bf16_f32 v10, v242, v243
	v_cvt_pk_bf16_f32 v11, v214, v215
	ds_write2_b64 v12, v[2:3], v[10:11] offset0:8 offset1:40
	s_waitcnt vmcnt(4)
	s_nop 1
	v_accvgpr_read_b32 v76, a232
	v_accvgpr_read_b32 v77, a233
	v_accvgpr_read_b32 v78, a234
	v_accvgpr_read_b32 v79, a235
	v_accvgpr_read_b32 v16, a236
	v_accvgpr_read_b32 v17, a237
	v_accvgpr_read_b32 v18, a238
	v_accvgpr_read_b32 v19, a239
	v_pk_mul_f32 v[2:3], v[250:251], v[16:17]
	v_pk_mul_f32 v[10:11], v[190:191], v[16:17]
	v_pk_fma_f32 v[2:3], v[190:191], v[76:77], v[2:3] neg_lo:[0,0,1] neg_hi:[0,0,1]
	v_pk_fma_f32 v[10:11], v[250:251], v[76:77], v[10:11]
	v_pk_mul_f32 v[2:3], v[50:51], v[2:3] op_sel_hi:[0,1]
	v_pk_mul_f32 v[190:191], v[50:51], v[10:11] op_sel_hi:[0,1]
	v_pk_mul_f32 v[10:11], v[248:249], v[18:19]
	v_cvt_pk_bf16_f32 v16, v190, v191
	v_pk_fma_f32 v[10:11], v[188:189], v[78:79], v[10:11] neg_lo:[0,0,1] neg_hi:[0,0,1]
	s_nop 0
	v_pk_mul_f32 v[250:251], v[50:51], v[10:11] op_sel_hi:[0,1]
	v_pk_mul_f32 v[10:11], v[188:189], v[18:19]
	s_nop 0
	v_pk_fma_f32 v[10:11], v[248:249], v[78:79], v[10:11]
	s_nop 0
	v_pk_mul_f32 v[188:189], v[50:51], v[10:11] op_sel_hi:[0,1]
	v_cvt_pk_bf16_f32 v10, v2, v3
	v_cvt_pk_bf16_f32 v11, v250, v251
	v_cvt_pk_bf16_f32 v17, v188, v189
	ds_write2_b64 v12, v[10:11], v[16:17] offset0:10 offset1:42
	s_waitcnt vmcnt(2)
	s_nop 1
	v_accvgpr_read_b32 v16, a240
	v_accvgpr_read_b32 v17, a241
	v_accvgpr_read_b32 v18, a242
	v_accvgpr_read_b32 v19, a243
	v_accvgpr_read_b32 v76, a244
	v_accvgpr_read_b32 v77, a245
	v_accvgpr_read_b32 v78, a246
	v_accvgpr_read_b32 v79, a247
	v_pk_mul_f32 v[10:11], v[240:241], v[76:77]
	s_nop 0
	v_pk_fma_f32 v[10:11], v[170:171], v[16:17], v[10:11] neg_lo:[0,0,1] neg_hi:[0,0,1]
	s_nop 0
	v_pk_mul_f32 v[248:249], v[50:51], v[10:11] op_sel_hi:[0,1]
	v_pk_mul_f32 v[10:11], v[170:171], v[76:77]
	s_nop 0
	v_pk_fma_f32 v[10:11], v[240:241], v[16:17], v[10:11]
	s_nop 0
	v_pk_mul_f32 v[170:171], v[50:51], v[10:11] op_sel_hi:[0,1]
	v_pk_mul_f32 v[10:11], v[238:239], v[78:79]
	v_cvt_pk_bf16_f32 v16, v170, v171
	v_pk_fma_f32 v[10:11], v[162:163], v[18:19], v[10:11] neg_lo:[0,0,1] neg_hi:[0,0,1]
	s_nop 0
	v_pk_mul_f32 v[240:241], v[50:51], v[10:11] op_sel_hi:[0,1]
	v_pk_mul_f32 v[10:11], v[162:163], v[78:79]
	s_nop 0
	v_pk_fma_f32 v[10:11], v[238:239], v[18:19], v[10:11]
	s_nop 0
	v_pk_mul_f32 v[162:163], v[50:51], v[10:11] op_sel_hi:[0,1]
	v_cvt_pk_bf16_f32 v10, v248, v249
	v_cvt_pk_bf16_f32 v11, v240, v241
	v_cvt_pk_bf16_f32 v17, v162, v163
	ds_write2_b64 v12, v[10:11], v[16:17] offset0:12 offset1:44
	s_nop 0
	s_waitcnt vmcnt(0)
	s_nop 1
	v_accvgpr_read_b32 v16, a248
	v_accvgpr_read_b32 v17, a249
	v_accvgpr_read_b32 v18, a250
	v_accvgpr_read_b32 v19, a251
	v_accvgpr_read_b32 v4, a252
	v_accvgpr_read_b32 v5, a253
	v_accvgpr_read_b32 v6, a254
	v_accvgpr_read_b32 v7, a255
	v_pk_mul_f32 v[10:11], v[230:231], v[4:5]
	v_pk_mul_f32 v[4:5], v[150:151], v[4:5]
	v_pk_fma_f32 v[10:11], v[150:151], v[16:17], v[10:11] neg_lo:[0,0,1] neg_hi:[0,0,1]
	v_pk_fma_f32 v[4:5], v[230:231], v[16:17], v[4:5]
	v_pk_mul_f32 v[238:239], v[50:51], v[10:11] op_sel_hi:[0,1]
	v_pk_mul_f32 v[224:225], v[50:51], v[4:5] op_sel_hi:[0,1]
	v_pk_mul_f32 v[4:5], v[222:223], v[6:7]
	s_nop 0
	v_pk_fma_f32 v[4:5], v[148:149], v[18:19], v[4:5] neg_lo:[0,0,1] neg_hi:[0,0,1]
	s_nop 0
	v_pk_mul_f32 v[230:231], v[50:51], v[4:5] op_sel_hi:[0,1]
	v_pk_mul_f32 v[4:5], v[148:149], v[6:7]
	v_cvt_pk_bf16_f32 v6, v224, v225
	v_pk_fma_f32 v[4:5], v[222:223], v[18:19], v[4:5]
	s_nop 0
	v_pk_mul_f32 v[222:223], v[50:51], v[4:5] op_sel_hi:[0,1]
	v_cvt_pk_bf16_f32 v4, v238, v239
	v_cvt_pk_bf16_f32 v5, v230, v231
	v_cvt_pk_bf16_f32 v7, v222, v223
	ds_write2_b64 v12, v[4:5], v[6:7] offset0:14 offset1:46
	v_or_b32_e32 v78, 0x60, v74
	v_or_b32_e32 v4, s66, v78
	v_lshlrev_b32_e32 v94, 9, v4
	v_lshl_add_u64 v[76:77], v[184:185], 0, v[94:95]
	v_lshl_add_u64 v[6:7], v[186:187], 0, v[94:95]
	global_load_dwordx4 a[192:195], v[76:77], off
	global_load_dwordx4 a[196:199], v[6:7], off
	global_load_dwordx4 a[200:203], v[76:77], off offset:32
	global_load_dwordx4 a[204:207], v[6:7], off offset:32
	global_load_dwordx4 a[208:211], v[76:77], off offset:64
	global_load_dwordx4 a[212:215], v[6:7], off offset:64
	global_load_dwordx4 a[216:219], v[76:77], off offset:96
	global_load_dwordx4 a[220:223], v[6:7], off offset:96
	global_load_dwordx4 a[224:227], v[76:77], off offset:128
	global_load_dwordx4 a[228:231], v[6:7], off offset:128
	global_load_dwordx4 a[232:235], v[76:77], off offset:160
	global_load_dwordx4 a[236:239], v[6:7], off offset:160
	global_load_dwordx4 a[240:243], v[76:77], off offset:192
	global_load_dwordx4 a[244:247], v[6:7], off offset:192
	global_load_dwordx4 a[248:251], v[76:77], off offset:224
	global_load_dwordx4 a[252:255], v[6:7], off offset:224
	v_accvgpr_read_b32 v61, a49
	v_accvgpr_read_b32 v4, a32
	v_accvgpr_read_b32 v60, a48
	v_accvgpr_read_b32 v5, a33
	s_waitcnt vmcnt(14)
	s_nop 1
	v_accvgpr_read_b32 v10, a192
	v_accvgpr_read_b32 v11, a193
	v_accvgpr_read_b32 v12, a194
	v_accvgpr_read_b32 v13, a195
	v_accvgpr_read_b32 v16, a196
	v_accvgpr_read_b32 v17, a197
	v_accvgpr_read_b32 v18, a198
	v_accvgpr_read_b32 v19, a199
	v_pk_mul_f32 v[74:75], v[60:61], v[16:17]
	s_nop 0
	v_pk_fma_f32 v[74:75], v[4:5], v[10:11], v[74:75] neg_lo:[0,0,1] neg_hi:[0,0,1]
	v_pk_mul_f32 v[4:5], v[4:5], v[16:17]
	v_pk_mul_f32 v[184:185], v[50:51], v[74:75] op_sel_hi:[0,1]
	v_pk_fma_f32 v[4:5], v[60:61], v[10:11], v[4:5]
	v_mad_u32_u24 v10, v78, s25, v51
	v_pk_mul_f32 v[148:149], v[50:51], v[4:5] op_sel_hi:[0,1]
	v_pk_mul_f32 v[4:5], v[192:193], v[18:19]
	s_nop 0
	v_pk_fma_f32 v[4:5], v[128:129], v[12:13], v[4:5] neg_lo:[0,0,1] neg_hi:[0,0,1]
	s_nop 0
	v_pk_mul_f32 v[150:151], v[50:51], v[4:5] op_sel_hi:[0,1]
	v_pk_mul_f32 v[4:5], v[128:129], v[18:19]
	s_nop 0
	v_pk_fma_f32 v[4:5], v[192:193], v[12:13], v[4:5]
	v_cvt_pk_bf16_f32 v12, v148, v149
	v_pk_mul_f32 v[128:129], v[50:51], v[4:5] op_sel_hi:[0,1]
	v_cvt_pk_bf16_f32 v4, v184, v185
	v_cvt_pk_bf16_f32 v5, v150, v151
	v_cvt_pk_bf16_f32 v13, v128, v129
	ds_write2_b64 v10, v[4:5], v[12:13] offset1:32
	s_waitcnt vmcnt(12)
	s_nop 1
	v_accvgpr_read_b32 v16, a200
	v_accvgpr_read_b32 v17, a201
	v_accvgpr_read_b32 v18, a202
	v_accvgpr_read_b32 v19, a203
	v_accvgpr_read_b32 v78, a204
	v_accvgpr_read_b32 v79, a205
	v_accvgpr_read_b32 v80, a206
	v_accvgpr_read_b32 v81, a207
	v_pk_mul_f32 v[4:5], v[166:167], v[78:79]
	s_nop 0
	v_pk_fma_f32 v[4:5], v[106:107], v[16:17], v[4:5] neg_lo:[0,0,1] neg_hi:[0,0,1]
	s_nop 0
	v_pk_mul_f32 v[186:187], v[50:51], v[4:5] op_sel_hi:[0,1]
	v_pk_mul_f32 v[4:5], v[106:107], v[78:79]
	s_nop 0
	v_pk_fma_f32 v[4:5], v[166:167], v[16:17], v[4:5]
	s_nop 0
	v_pk_mul_f32 v[106:107], v[50:51], v[4:5] op_sel_hi:[0,1]
	v_pk_mul_f32 v[4:5], v[160:161], v[80:81]
	v_cvt_pk_bf16_f32 v12, v106, v107
	v_pk_fma_f32 v[4:5], v[98:99], v[18:19], v[4:5] neg_lo:[0,0,1] neg_hi:[0,0,1]
	s_nop 0
	v_pk_mul_f32 v[166:167], v[50:51], v[4:5] op_sel_hi:[0,1]
	v_pk_mul_f32 v[4:5], v[98:99], v[80:81]
	s_nop 0
	v_pk_fma_f32 v[4:5], v[160:161], v[18:19], v[4:5]
	s_nop 0
	v_pk_mul_f32 v[98:99], v[50:51], v[4:5] op_sel_hi:[0,1]
	v_cvt_pk_bf16_f32 v4, v186, v187
	v_cvt_pk_bf16_f32 v5, v166, v167
	v_cvt_pk_bf16_f32 v13, v98, v99
	ds_write2_b64 v10, v[4:5], v[12:13] offset0:2 offset1:34
	s_waitcnt vmcnt(10)
	s_nop 1
	v_accvgpr_read_b32 v16, a208
	v_accvgpr_read_b32 v17, a209
	v_accvgpr_read_b32 v18, a210
	v_accvgpr_read_b32 v19, a211
	v_accvgpr_read_b32 v78, a212
	v_accvgpr_read_b32 v79, a213
	v_accvgpr_read_b32 v80, a214
	v_accvgpr_read_b32 v81, a215
	v_pk_mul_f32 v[4:5], v[142:143], v[78:79]
	s_nop 0
	v_pk_fma_f32 v[4:5], v[96:97], v[16:17], v[4:5] neg_lo:[0,0,1] neg_hi:[0,0,1]
	s_nop 0
	v_pk_mul_f32 v[160:161], v[50:51], v[4:5] op_sel_hi:[0,1]
	v_pk_mul_f32 v[4:5], v[96:97], v[78:79]
	s_nop 0
	v_pk_fma_f32 v[4:5], v[142:143], v[16:17], v[4:5]
	s_nop 0
	v_pk_mul_f32 v[96:97], v[50:51], v[4:5] op_sel_hi:[0,1]
	v_pk_mul_f32 v[4:5], v[140:141], v[80:81]
	v_cvt_pk_bf16_f32 v12, v96, v97
	v_pk_fma_f32 v[4:5], v[86:87], v[18:19], v[4:5] neg_lo:[0,0,1] neg_hi:[0,0,1]
	s_nop 0
	v_pk_mul_f32 v[142:143], v[50:51], v[4:5] op_sel_hi:[0,1]
	v_pk_mul_f32 v[4:5], v[86:87], v[80:81]
	s_nop 0
	v_pk_fma_f32 v[4:5], v[140:141], v[18:19], v[4:5]
	s_nop 0
	v_pk_mul_f32 v[20:21], v[50:51], v[4:5] op_sel_hi:[0,1]
	v_cvt_pk_bf16_f32 v4, v160, v161
	v_cvt_pk_bf16_f32 v5, v142, v143
	v_cvt_pk_bf16_f32 v13, v20, v21
	ds_write2_b64 v10, v[4:5], v[12:13] offset0:4 offset1:36
	s_waitcnt vmcnt(8)
	s_nop 1
	v_accvgpr_read_b32 v16, a216
	v_accvgpr_read_b32 v17, a217
	v_accvgpr_read_b32 v18, a218
	v_accvgpr_read_b32 v19, a219
	v_accvgpr_read_b32 v78, a220
	v_accvgpr_read_b32 v79, a221
	v_accvgpr_read_b32 v80, a222
	v_accvgpr_read_b32 v81, a223
	v_pk_mul_f32 v[4:5], v[126:127], v[78:79]
	s_nop 0
	v_pk_fma_f32 v[4:5], v[90:91], v[16:17], v[4:5] neg_lo:[0,0,1] neg_hi:[0,0,1]
	s_nop 0
	v_pk_mul_f32 v[140:141], v[50:51], v[4:5] op_sel_hi:[0,1]
	v_pk_mul_f32 v[4:5], v[90:91], v[78:79]
	s_nop 0
	v_pk_fma_f32 v[4:5], v[126:127], v[16:17], v[4:5]
	s_nop 0
	v_pk_mul_f32 v[90:91], v[50:51], v[4:5] op_sel_hi:[0,1]
	v_pk_mul_f32 v[4:5], v[124:125], v[80:81]
	v_cvt_pk_bf16_f32 v12, v90, v91
	v_pk_fma_f32 v[4:5], v[88:89], v[18:19], v[4:5] neg_lo:[0,0,1] neg_hi:[0,0,1]
	s_nop 0
	v_pk_mul_f32 v[126:127], v[50:51], v[4:5] op_sel_hi:[0,1]
	v_pk_mul_f32 v[4:5], v[88:89], v[80:81]
	s_nop 0
	v_pk_fma_f32 v[4:5], v[124:125], v[18:19], v[4:5]
	s_nop 0
	v_pk_mul_f32 v[88:89], v[50:51], v[4:5] op_sel_hi:[0,1]
	v_cvt_pk_bf16_f32 v4, v140, v141
	v_cvt_pk_bf16_f32 v5, v126, v127
	v_cvt_pk_bf16_f32 v13, v88, v89
	ds_write2_b64 v10, v[4:5], v[12:13] offset0:6 offset1:38
	v_accvgpr_read_b32 v12, a16
	v_accvgpr_read_b32 v5, a1
	v_accvgpr_read_b32 v13, a17
	v_accvgpr_read_b32 v4, a0
	s_waitcnt vmcnt(6)
	s_nop 1
	v_accvgpr_read_b32 v16, a224
	v_accvgpr_read_b32 v17, a225
	v_accvgpr_read_b32 v18, a226
	v_accvgpr_read_b32 v19, a227
	v_accvgpr_read_b32 v78, a228
	v_accvgpr_read_b32 v79, a229
	v_accvgpr_read_b32 v80, a230
	v_accvgpr_read_b32 v81, a231
	v_pk_mul_f32 v[60:61], v[12:13], v[78:79]
	s_nop 0
	v_pk_fma_f32 v[60:61], v[4:5], v[16:17], v[60:61] neg_lo:[0,0,1] neg_hi:[0,0,1]
	v_pk_mul_f32 v[4:5], v[4:5], v[78:79]
	v_pk_mul_f32 v[192:193], v[50:51], v[60:61] op_sel_hi:[0,1]
	v_pk_fma_f32 v[4:5], v[12:13], v[16:17], v[4:5]
	s_nop 0
	v_pk_mul_f32 v[124:125], v[50:51], v[4:5] op_sel_hi:[0,1]
	v_pk_mul_f32 v[4:5], v[138:139], v[80:81]
	v_pk_mul_f32 v[12:13], v[92:93], v[80:81]
	v_pk_fma_f32 v[4:5], v[92:93], v[18:19], v[4:5] neg_lo:[0,0,1] neg_hi:[0,0,1]
	v_pk_fma_f32 v[12:13], v[138:139], v[18:19], v[12:13]
	v_pk_mul_f32 v[4:5], v[50:51], v[4:5] op_sel_hi:[0,1]
	v_pk_mul_f32 v[92:93], v[50:51], v[12:13] op_sel_hi:[0,1]
	v_cvt_pk_bf16_f32 v12, v192, v193
	v_cvt_pk_bf16_f32 v13, v4, v5
	v_cvt_pk_bf16_f32 v16, v124, v125
	v_cvt_pk_bf16_f32 v17, v92, v93
	ds_write2_b64 v10, v[12:13], v[16:17] offset0:8 offset1:40
	s_waitcnt vmcnt(4)
	s_nop 1
	v_accvgpr_read_b32 v16, a232
	v_accvgpr_read_b32 v17, a233
	v_accvgpr_read_b32 v18, a234
	v_accvgpr_read_b32 v19, a235
	v_accvgpr_read_b32 v78, a236
	v_accvgpr_read_b32 v79, a237
	v_accvgpr_read_b32 v80, a238
	v_accvgpr_read_b32 v81, a239
	v_pk_mul_f32 v[12:13], v[122:123], v[78:79]
	s_nop 0
	v_pk_fma_f32 v[12:13], v[82:83], v[16:17], v[12:13] neg_lo:[0,0,1] neg_hi:[0,0,1]
	s_nop 0
	v_pk_mul_f32 v[138:139], v[50:51], v[12:13] op_sel_hi:[0,1]
	v_pk_mul_f32 v[12:13], v[82:83], v[78:79]
	s_nop 0
	v_pk_fma_f32 v[12:13], v[122:123], v[16:17], v[12:13]
	s_nop 0
	v_pk_mul_f32 v[86:87], v[50:51], v[12:13] op_sel_hi:[0,1]
	v_pk_mul_f32 v[12:13], v[116:117], v[80:81]
	v_cvt_pk_bf16_f32 v16, v86, v87
	v_pk_fma_f32 v[12:13], v[84:85], v[18:19], v[12:13] neg_lo:[0,0,1] neg_hi:[0,0,1]
	v_accvgpr_read_b32 v61, a39
	v_pk_mul_f32 v[122:123], v[50:51], v[12:13] op_sel_hi:[0,1]
	v_pk_mul_f32 v[12:13], v[84:85], v[80:81]
	v_accvgpr_read_b32 v60, a38
	v_pk_fma_f32 v[12:13], v[116:117], v[18:19], v[12:13]
	s_nop 0
	v_pk_mul_f32 v[84:85], v[50:51], v[12:13] op_sel_hi:[0,1]
	v_cvt_pk_bf16_f32 v12, v138, v139
	v_cvt_pk_bf16_f32 v13, v122, v123
	v_cvt_pk_bf16_f32 v17, v84, v85
	ds_write2_b64 v10, v[12:13], v[16:17] offset0:10 offset1:42
	s_waitcnt vmcnt(2)
	s_nop 1
	v_accvgpr_read_b32 v16, a240
	v_accvgpr_read_b32 v17, a241
	v_accvgpr_read_b32 v18, a242
	v_accvgpr_read_b32 v19, a243
	v_accvgpr_read_b32 v78, a244
	v_accvgpr_read_b32 v79, a245
	v_accvgpr_read_b32 v80, a246
	v_accvgpr_read_b32 v81, a247
	v_pk_mul_f32 v[12:13], v[102:103], v[78:79]
	s_nop 0
	v_pk_fma_f32 v[12:13], v[60:61], v[16:17], v[12:13] neg_lo:[0,0,1] neg_hi:[0,0,1]
	s_nop 0
	v_pk_mul_f32 v[116:117], v[50:51], v[12:13] op_sel_hi:[0,1]
	v_pk_mul_f32 v[12:13], v[60:61], v[78:79]
	s_nop 0
	v_pk_fma_f32 v[12:13], v[102:103], v[16:17], v[12:13]
	s_nop 0
	v_pk_mul_f32 v[82:83], v[50:51], v[12:13] op_sel_hi:[0,1]
	v_accvgpr_read_b32 v16, a36
	v_pk_mul_f32 v[12:13], v[8:9], v[80:81]
	v_accvgpr_read_b32 v17, a37
	v_pk_fma_f32 v[12:13], v[16:17], v[18:19], v[12:13] neg_lo:[0,0,1] neg_hi:[0,0,1]
	v_accvgpr_read_b32 v61, a13
	v_pk_mul_f32 v[102:103], v[50:51], v[12:13] op_sel_hi:[0,1]
	v_pk_mul_f32 v[12:13], v[16:17], v[80:81]
	v_accvgpr_read_b32 v60, a12
	v_pk_fma_f32 v[8:9], v[8:9], v[18:19], v[12:13]
	v_cvt_pk_bf16_f32 v12, v82, v83
	v_pk_mul_f32 v[74:75], v[50:51], v[8:9] op_sel_hi:[0,1]
	v_cvt_pk_bf16_f32 v8, v116, v117
	v_cvt_pk_bf16_f32 v9, v102, v103
	v_cvt_pk_bf16_f32 v13, v74, v75
	ds_write2_b64 v10, v[8:9], v[12:13] offset0:12 offset1:44
	s_nop 0
	s_waitcnt vmcnt(0)
	s_nop 1
	v_accvgpr_read_b32 v16, a248
	v_accvgpr_read_b32 v17, a249
	v_accvgpr_read_b32 v18, a250
	v_accvgpr_read_b32 v19, a251
	v_accvgpr_read_b32 v6, a252
	v_accvgpr_read_b32 v7, a253
	v_accvgpr_read_b32 v8, a254
	v_accvgpr_read_b32 v9, a255
	v_pk_mul_f32 v[12:13], v[56:57], v[6:7]
	v_pk_mul_f32 v[6:7], v[60:61], v[6:7]
	v_pk_fma_f32 v[12:13], v[60:61], v[16:17], v[12:13] neg_lo:[0,0,1] neg_hi:[0,0,1]
	v_pk_fma_f32 v[6:7], v[56:57], v[16:17], v[6:7]
	v_pk_mul_f32 v[80:81], v[50:51], v[12:13] op_sel_hi:[0,1]
	v_pk_mul_f32 v[56:57], v[50:51], v[6:7] op_sel_hi:[0,1]
	v_accvgpr_read_b32 v12, a14
	v_pk_mul_f32 v[6:7], v[46:47], v[8:9]
	v_accvgpr_read_b32 v13, a15
	v_pk_fma_f32 v[6:7], v[12:13], v[18:19], v[6:7] neg_lo:[0,0,1] neg_hi:[0,0,1]
	s_nop 0
	v_pk_mul_f32 v[78:79], v[50:51], v[6:7] op_sel_hi:[0,1]
	v_pk_mul_f32 v[6:7], v[12:13], v[8:9]
	v_cvt_pk_bf16_f32 v8, v56, v57
	v_pk_fma_f32 v[6:7], v[46:47], v[18:19], v[6:7]
	s_nop 0
	v_pk_mul_f32 v[46:47], v[50:51], v[6:7] op_sel_hi:[0,1]
	v_cvt_pk_bf16_f32 v6, v80, v81
	v_cvt_pk_bf16_f32 v7, v78, v79
	v_cvt_pk_bf16_f32 v9, v46, v47
	ds_write2_b64 v10, v[6:7], v[8:9] offset0:14 offset1:46
	s_and_b64 s[10:11], vcc, exec
	s_cselect_b32 s10, s36, 0x16100000
	s_add_u32 s12, s92, s10
	s_addc_u32 s13, s93, 0
	s_lshl_b64 s[10:11], s[40:41], 1
	s_add_u32 s12, s12, s10
	s_addc_u32 s11, s13, s11
	s_lshl_b32 s10, s4, 8
	s_lshl_b32 s13, s4, 9
	s_add_u32 s12, s12, s13
	s_addc_u32 s13, s11, 0
	s_mov_b32 s11, 0
	s_waitcnt lgkmcnt(0)
	s_barrier
	s_nop 0
	v_mbcnt_lo_u32_b32 v6, -1, s11
	v_mbcnt_hi_u32_b32 v6, -1, v6
	v_or_b32_e32 v8, s60, v6
	v_lshlrev_b32_e32 v6, 4, v6
	v_and_b32_e32 v94, 0x1f0, v6
	v_lshl_add_u64 v[6:7], s[12:13], 0, v[94:95]
